# scan: block-boundary DPP gaps filled with that step's LDS reads, staging waves poll less often
# baseline (speedup 1.0000x reference)
.Lsc_S_loop:
	s_waitcnt lgkmcnt(6)
	v_pk_fma_f32 v[10:11], v[80:81], v[30:31], v[16:17] op_sel_hi:[1,0,1] neg_lo:[0,1,0] neg_hi:[0,1,0]
	v_pk_fma_f32 v[8:9], v[82:83], v[30:31], v[18:19] op_sel_hi:[1,0,1] neg_lo:[0,1,0] neg_hi:[0,1,0]
	v_pk_mul_f32 v[24:25], v[10:11], v[84:85] op_sel:[0,0] op_sel_hi:[0,1]
	v_pk_fma_f32 v[24:25], v[10:11], v[86:87], v[24:25] op_sel:[1,0,0] op_sel_hi:[1,1,1]
	v_pk_fma_f32 v[24:25], v[8:9], v[88:89], v[24:25] op_sel:[0,0,0] op_sel_hi:[0,1,1]
	v_pk_fma_f32 v[24:25], v[8:9], v[90:91], v[24:25] op_sel:[1,0,0] op_sel_hi:[1,1,1]
	v_pk_fma_f32 v[16:17], v[92:93], v[156:157], v[10:11] op_sel:[0,1,0] op_sel_hi:[1,1,1]
	v_pk_fma_f32 v[18:19], v[94:95], v[156:157], v[8:9] op_sel:[0,1,0] op_sel_hi:[1,1,1]
	v_add_f32_dpp v15, v24, v24 row_ror:8 row_mask:0xf bank_mask:0xf bound_ctrl:1
	v_add_f32_dpp v32, v25, v25 row_ror:8 row_mask:0xf bank_mask:0xf bound_ctrl:1
	ds_read_b128 v[124:127], v34 offset:3072
	v_add_f32_dpp v15, v15, v15 row_ror:4 row_mask:0xf bank_mask:0xf bound_ctrl:1
	ds_read_b128 v[128:131], v34 offset:3328
	ds_read_b128 v[132:135], v34 offset:3584
	v_add_f32_dpp v15, v15, v15 row_ror:2 row_mask:0xf bank_mask:0xf bound_ctrl:1
	ds_read_b128 v[136:139], v34 offset:3840
	ds_read_b128 v[160:163], v35 offset:16
	v_add_f32_dpp v30, v15, v15 row_ror:1 row_mask:0xf bank_mask:0xf bound_ctrl:1
	s_waitcnt lgkmcnt(5)
	v_pk_fma_f32 v[10:11], v[96:97], v[30:31], v[16:17] op_sel_hi:[1,0,1] neg_lo:[0,1,0] neg_hi:[0,1,0]
	v_pk_fma_f32 v[8:9], v[98:99], v[30:31], v[18:19] op_sel_hi:[1,0,1] neg_lo:[0,1,0] neg_hi:[0,1,0]
	v_pk_mul_f32 v[24:25], v[10:11], v[100:101] op_sel:[0,0] op_sel_hi:[0,1]
	v_pk_fma_f32 v[24:25], v[10:11], v[102:103], v[24:25] op_sel:[1,0,0] op_sel_hi:[1,1,1]
	v_pk_fma_f32 v[24:25], v[8:9], v[104:105], v[24:25] op_sel:[0,0,0] op_sel_hi:[0,1,1]
	v_pk_fma_f32 v[24:25], v[8:9], v[106:107], v[24:25] op_sel:[1,0,0] op_sel_hi:[1,1,1]
	v_pk_fma_f32 v[16:17], v[108:109], v[158:159], v[10:11] op_sel_hi:[1,0,1]
	v_pk_fma_f32 v[18:19], v[110:111], v[158:159], v[8:9] op_sel_hi:[1,0,1]
	v_add_f32_dpp v15, v24, v24 row_ror:8 row_mask:0xf bank_mask:0xf bound_ctrl:1
	v_add_f32_dpp v33, v25, v25 row_ror:8 row_mask:0xf bank_mask:0xf bound_ctrl:1
	ds_read_b128 v[76:79], v34 offset:4096
	v_add_f32_dpp v15, v15, v15 row_ror:4 row_mask:0xf bank_mask:0xf bound_ctrl:1
	ds_read_b128 v[80:83], v34 offset:4352
	ds_read_b128 v[84:87], v34 offset:4608
	v_add_f32_dpp v15, v15, v15 row_ror:2 row_mask:0xf bank_mask:0xf bound_ctrl:1
	ds_read_b128 v[88:91], v34 offset:4864
	s_nop 0
	v_add_f32_dpp v30, v15, v15 row_ror:1 row_mask:0xf bank_mask:0xf bound_ctrl:1
	ds_write2st64_b32 v37, v32, v33 offset0:0 offset1:2
	s_waitcnt lgkmcnt(5)
	v_pk_fma_f32 v[10:11], v[112:113], v[30:31], v[16:17] op_sel_hi:[1,0,1] neg_lo:[0,1,0] neg_hi:[0,1,0]
	v_pk_fma_f32 v[8:9], v[114:115], v[30:31], v[18:19] op_sel_hi:[1,0,1] neg_lo:[0,1,0] neg_hi:[0,1,0]
	v_pk_mul_f32 v[24:25], v[10:11], v[116:117] op_sel:[0,0] op_sel_hi:[0,1]
	v_pk_fma_f32 v[24:25], v[10:11], v[118:119], v[24:25] op_sel:[1,0,0] op_sel_hi:[1,1,1]
	v_pk_fma_f32 v[24:25], v[8:9], v[120:121], v[24:25] op_sel:[0,0,0] op_sel_hi:[0,1,1]
	v_pk_fma_f32 v[24:25], v[8:9], v[122:123], v[24:25] op_sel:[1,0,0] op_sel_hi:[1,1,1]
	v_pk_fma_f32 v[16:17], v[124:125], v[158:159], v[10:11] op_sel:[0,1,0] op_sel_hi:[1,1,1]
	v_pk_fma_f32 v[18:19], v[126:127], v[158:159], v[8:9] op_sel:[0,1,0] op_sel_hi:[1,1,1]
	v_add_f32_dpp v15, v24, v24 row_ror:8 row_mask:0xf bank_mask:0xf bound_ctrl:1
	v_add_f32_dpp v32, v25, v25 row_ror:8 row_mask:0xf bank_mask:0xf bound_ctrl:1
	ds_read_b128 v[92:95], v34 offset:5120
	v_add_f32_dpp v15, v15, v15 row_ror:4 row_mask:0xf bank_mask:0xf bound_ctrl:1
	ds_read_b128 v[96:99], v34 offset:5376
	ds_read_b128 v[100:103], v34 offset:5632
	v_add_f32_dpp v15, v15, v15 row_ror:2 row_mask:0xf bank_mask:0xf bound_ctrl:1
	ds_read_b128 v[104:107], v34 offset:5888
	s_nop 0
	v_add_f32_dpp v30, v15, v15 row_ror:1 row_mask:0xf bank_mask:0xf bound_ctrl:1
	s_waitcnt lgkmcnt(4)
	v_pk_fma_f32 v[10:11], v[128:129], v[30:31], v[16:17] op_sel_hi:[1,0,1] neg_lo:[0,1,0] neg_hi:[0,1,0]
	v_pk_fma_f32 v[8:9], v[130:131], v[30:31], v[18:19] op_sel_hi:[1,0,1] neg_lo:[0,1,0] neg_hi:[0,1,0]
	v_pk_mul_f32 v[24:25], v[10:11], v[132:133] op_sel:[0,0] op_sel_hi:[0,1]
	v_pk_fma_f32 v[24:25], v[10:11], v[134:135], v[24:25] op_sel:[1,0,0] op_sel_hi:[1,1,1]
	v_pk_fma_f32 v[24:25], v[8:9], v[136:137], v[24:25] op_sel:[0,0,0] op_sel_hi:[0,1,1]
	v_pk_fma_f32 v[24:25], v[8:9], v[138:139], v[24:25] op_sel:[1,0,0] op_sel_hi:[1,1,1]
	v_pk_fma_f32 v[16:17], v[76:77], v[160:161], v[10:11] op_sel_hi:[1,0,1]
	v_pk_fma_f32 v[18:19], v[78:79], v[160:161], v[8:9] op_sel_hi:[1,0,1]
	v_add_f32_dpp v15, v24, v24 row_ror:8 row_mask:0xf bank_mask:0xf bound_ctrl:1
	v_add_f32_dpp v33, v25, v25 row_ror:8 row_mask:0xf bank_mask:0xf bound_ctrl:1
	ds_read_b128 v[108:111], v34 offset:6144
	v_add_f32_dpp v15, v15, v15 row_ror:4 row_mask:0xf bank_mask:0xf bound_ctrl:1
	ds_read_b128 v[112:115], v34 offset:6400
	ds_read_b128 v[116:119], v34 offset:6656
	v_add_f32_dpp v15, v15, v15 row_ror:2 row_mask:0xf bank_mask:0xf bound_ctrl:1
	ds_read_b128 v[120:123], v34 offset:6912
	ds_read_b128 v[140:143], v34 offset:33792
	v_add_f32_dpp v30, v15, v15 row_ror:1 row_mask:0xf bank_mask:0xf bound_ctrl:1
	ds_write2st64_b32 v37, v32, v33 offset0:4 offset1:6
	s_waitcnt lgkmcnt(6)
	v_pk_fma_f32 v[10:11], v[80:81], v[30:31], v[16:17] op_sel_hi:[1,0,1] neg_lo:[0,1,0] neg_hi:[0,1,0]
	v_pk_fma_f32 v[8:9], v[82:83], v[30:31], v[18:19] op_sel_hi:[1,0,1] neg_lo:[0,1,0] neg_hi:[0,1,0]
	v_pk_mul_f32 v[24:25], v[10:11], v[84:85] op_sel:[0,0] op_sel_hi:[0,1]
	v_pk_fma_f32 v[24:25], v[10:11], v[86:87], v[24:25] op_sel:[1,0,0] op_sel_hi:[1,1,1]
	v_pk_fma_f32 v[24:25], v[8:9], v[88:89], v[24:25] op_sel:[0,0,0] op_sel_hi:[0,1,1]
	v_pk_fma_f32 v[24:25], v[8:9], v[90:91], v[24:25] op_sel:[1,0,0] op_sel_hi:[1,1,1]
	v_pk_fma_f32 v[16:17], v[92:93], v[160:161], v[10:11] op_sel:[0,1,0] op_sel_hi:[1,1,1]
	v_pk_fma_f32 v[18:19], v[94:95], v[160:161], v[8:9] op_sel:[0,1,0] op_sel_hi:[1,1,1]
	v_add_f32_dpp v15, v24, v24 row_ror:8 row_mask:0xf bank_mask:0xf bound_ctrl:1
	v_add_f32_dpp v32, v25, v25 row_ror:8 row_mask:0xf bank_mask:0xf bound_ctrl:1
	ds_read_b128 v[124:127], v34 offset:7168
	v_add_f32_dpp v15, v15, v15 row_ror:4 row_mask:0xf bank_mask:0xf bound_ctrl:1
	ds_read_b128 v[128:131], v34 offset:7424
	ds_read_b128 v[132:135], v34 offset:7680
	v_add_f32_dpp v15, v15, v15 row_ror:2 row_mask:0xf bank_mask:0xf bound_ctrl:1
	ds_read_b128 v[136:139], v34 offset:7936
	ds_read_b128 v[156:159], v35 offset:32
	v_add_f32_dpp v30, v15, v15 row_ror:1 row_mask:0xf bank_mask:0xf bound_ctrl:1
	s_waitcnt lgkmcnt(5)
	v_pk_fma_f32 v[10:11], v[96:97], v[30:31], v[16:17] op_sel_hi:[1,0,1] neg_lo:[0,1,0] neg_hi:[0,1,0]
	v_pk_fma_f32 v[8:9], v[98:99], v[30:31], v[18:19] op_sel_hi:[1,0,1] neg_lo:[0,1,0] neg_hi:[0,1,0]
	v_pk_mul_f32 v[24:25], v[10:11], v[100:101] op_sel:[0,0] op_sel_hi:[0,1]
	v_pk_fma_f32 v[24:25], v[10:11], v[102:103], v[24:25] op_sel:[1,0,0] op_sel_hi:[1,1,1]
	v_pk_fma_f32 v[24:25], v[8:9], v[104:105], v[24:25] op_sel:[0,0,0] op_sel_hi:[0,1,1]
	v_pk_fma_f32 v[24:25], v[8:9], v[106:107], v[24:25] op_sel:[1,0,0] op_sel_hi:[1,1,1]
	v_pk_fma_f32 v[16:17], v[108:109], v[162:163], v[10:11] op_sel_hi:[1,0,1]
	v_pk_fma_f32 v[18:19], v[110:111], v[162:163], v[8:9] op_sel_hi:[1,0,1]
	v_add_f32_dpp v15, v24, v24 row_ror:8 row_mask:0xf bank_mask:0xf bound_ctrl:1
	v_add_f32_dpp v33, v25, v25 row_ror:8 row_mask:0xf bank_mask:0xf bound_ctrl:1
	ds_read_b128 v[76:79], v34 offset:8192
	v_add_f32_dpp v15, v15, v15 row_ror:4 row_mask:0xf bank_mask:0xf bound_ctrl:1
	ds_read_b128 v[80:83], v34 offset:8448
	ds_read_b128 v[84:87], v34 offset:8704
	v_add_f32_dpp v15, v15, v15 row_ror:2 row_mask:0xf bank_mask:0xf bound_ctrl:1
	ds_read_b128 v[88:91], v34 offset:8960
	ds_read_b128 v[144:147], v34 offset:33024
	v_add_f32_dpp v30, v15, v15 row_ror:1 row_mask:0xf bank_mask:0xf bound_ctrl:1
	ds_write2st64_b32 v37, v32, v33 offset0:8 offset1:10
	s_waitcnt lgkmcnt(6)
	v_pk_fma_f32 v[10:11], v[112:113], v[30:31], v[16:17] op_sel_hi:[1,0,1] neg_lo:[0,1,0] neg_hi:[0,1,0]
	v_pk_fma_f32 v[8:9], v[114:115], v[30:31], v[18:19] op_sel_hi:[1,0,1] neg_lo:[0,1,0] neg_hi:[0,1,0]
	v_pk_mul_f32 v[24:25], v[10:11], v[116:117] op_sel:[0,0] op_sel_hi:[0,1]
	v_pk_fma_f32 v[24:25], v[10:11], v[118:119], v[24:25] op_sel:[1,0,0] op_sel_hi:[1,1,1]
	v_pk_fma_f32 v[24:25], v[8:9], v[120:121], v[24:25] op_sel:[0,0,0] op_sel_hi:[0,1,1]
	v_pk_fma_f32 v[24:25], v[8:9], v[122:123], v[24:25] op_sel:[1,0,0] op_sel_hi:[1,1,1]
	v_pk_fma_f32 v[16:17], v[124:125], v[162:163], v[10:11] op_sel:[0,1,0] op_sel_hi:[1,1,1]
	v_pk_fma_f32 v[18:19], v[126:127], v[162:163], v[8:9] op_sel:[0,1,0] op_sel_hi:[1,1,1]
	v_add_f32_dpp v15, v24, v24 row_ror:8 row_mask:0xf bank_mask:0xf bound_ctrl:1
	v_add_f32_dpp v32, v25, v25 row_ror:8 row_mask:0xf bank_mask:0xf bound_ctrl:1
	ds_read_b128 v[92:95], v34 offset:9216
	v_add_f32_dpp v15, v15, v15 row_ror:4 row_mask:0xf bank_mask:0xf bound_ctrl:1
	ds_read_b128 v[96:99], v34 offset:9472
	ds_read_b128 v[100:103], v34 offset:9728
	v_add_f32_dpp v15, v15, v15 row_ror:2 row_mask:0xf bank_mask:0xf bound_ctrl:1
	ds_read_b128 v[104:107], v34 offset:9984
	s_nop 0
	v_add_f32_dpp v30, v15, v15 row_ror:1 row_mask:0xf bank_mask:0xf bound_ctrl:1
	s_waitcnt lgkmcnt(4)
	v_pk_fma_f32 v[10:11], v[128:129], v[30:31], v[16:17] op_sel_hi:[1,0,1] neg_lo:[0,1,0] neg_hi:[0,1,0]
	v_pk_fma_f32 v[8:9], v[130:131], v[30:31], v[18:19] op_sel_hi:[1,0,1] neg_lo:[0,1,0] neg_hi:[0,1,0]
	v_pk_mul_f32 v[24:25], v[10:11], v[132:133] op_sel:[0,0] op_sel_hi:[0,1]
	v_pk_fma_f32 v[24:25], v[10:11], v[134:135], v[24:25] op_sel:[1,0,0] op_sel_hi:[1,1,1]
	v_pk_fma_f32 v[24:25], v[8:9], v[136:137], v[24:25] op_sel:[0,0,0] op_sel_hi:[0,1,1]
	v_pk_fma_f32 v[24:25], v[8:9], v[138:139], v[24:25] op_sel:[1,0,0] op_sel_hi:[1,1,1]
	s_nop 1
	v_add_f32_dpp v33, v25, v25 row_ror:8 row_mask:0xf bank_mask:0xf bound_ctrl:1
	ds_write2st64_b32 v37, v32, v33 offset0:12 offset1:14
	v_pk_mul_f32 v[10:11], v[10:11], v[140:141]
	v_pk_mul_f32 v[8:9], v[8:9], v[142:143]
	v_pk_mul_f32 v[24:25], v[10:11], v[144:145]
	v_pk_fma_f32 v[24:25], v[8:9], v[146:147], v[24:25]
	v_add_f32_e32 v24, v24, v25
	v_pk_fma_f32 v[16:17], v[76:77], v[156:157], v[10:11] op_sel_hi:[1,0,1]
	v_pk_fma_f32 v[18:19], v[78:79], v[156:157], v[8:9] op_sel_hi:[1,0,1]
	v_add_f32_dpp v15, v24, v24 row_ror:8 row_mask:0xf bank_mask:0xf bound_ctrl:1
	ds_read_b128 v[108:111], v34 offset:10240
	ds_read_b128 v[112:115], v34 offset:10496
	v_add_f32_dpp v15, v15, v15 row_ror:4 row_mask:0xf bank_mask:0xf bound_ctrl:1
	ds_read_b128 v[116:119], v34 offset:10752
	ds_read_b128 v[120:123], v34 offset:11008
	v_add_f32_dpp v15, v15, v15 row_ror:2 row_mask:0xf bank_mask:0xf bound_ctrl:1
	s_nop 1
	v_add_f32_dpp v30, v15, v15 row_ror:1 row_mask:0xf bank_mask:0xf bound_ctrl:1
	s_waitcnt lgkmcnt(5)
	v_pk_fma_f32 v[10:11], v[80:81], v[30:31], v[16:17] op_sel_hi:[1,0,1] neg_lo:[0,1,0] neg_hi:[0,1,0]
	v_pk_fma_f32 v[8:9], v[82:83], v[30:31], v[18:19] op_sel_hi:[1,0,1] neg_lo:[0,1,0] neg_hi:[0,1,0]
	v_pk_mul_f32 v[24:25], v[10:11], v[84:85] op_sel:[0,0] op_sel_hi:[0,1]
	v_pk_fma_f32 v[24:25], v[10:11], v[86:87], v[24:25] op_sel:[1,0,0] op_sel_hi:[1,1,1]
	v_pk_fma_f32 v[24:25], v[8:9], v[88:89], v[24:25] op_sel:[0,0,0] op_sel_hi:[0,1,1]
	v_pk_fma_f32 v[24:25], v[8:9], v[90:91], v[24:25] op_sel:[1,0,0] op_sel_hi:[1,1,1]
	v_pk_fma_f32 v[16:17], v[92:93], v[156:157], v[10:11] op_sel:[0,1,0] op_sel_hi:[1,1,1]
	v_pk_fma_f32 v[18:19], v[94:95], v[156:157], v[8:9] op_sel:[0,1,0] op_sel_hi:[1,1,1]
	v_add_f32_dpp v15, v24, v24 row_ror:8 row_mask:0xf bank_mask:0xf bound_ctrl:1
	v_add_f32_dpp v32, v25, v25 row_ror:8 row_mask:0xf bank_mask:0xf bound_ctrl:1
	ds_read_b128 v[124:127], v34 offset:11264
	v_add_f32_dpp v15, v15, v15 row_ror:4 row_mask:0xf bank_mask:0xf bound_ctrl:1
	ds_read_b128 v[128:131], v34 offset:11520
	ds_read_b128 v[132:135], v34 offset:11776
	v_add_f32_dpp v15, v15, v15 row_ror:2 row_mask:0xf bank_mask:0xf bound_ctrl:1
	ds_read_b128 v[136:139], v34 offset:12032
	ds_read_b128 v[160:163], v35 offset:48
	v_add_f32_dpp v30, v15, v15 row_ror:1 row_mask:0xf bank_mask:0xf bound_ctrl:1
	s_waitcnt lgkmcnt(5)
	v_pk_fma_f32 v[10:11], v[96:97], v[30:31], v[16:17] op_sel_hi:[1,0,1] neg_lo:[0,1,0] neg_hi:[0,1,0]
	v_pk_fma_f32 v[8:9], v[98:99], v[30:31], v[18:19] op_sel_hi:[1,0,1] neg_lo:[0,1,0] neg_hi:[0,1,0]
	v_pk_mul_f32 v[24:25], v[10:11], v[100:101] op_sel:[0,0] op_sel_hi:[0,1]
	v_pk_fma_f32 v[24:25], v[10:11], v[102:103], v[24:25] op_sel:[1,0,0] op_sel_hi:[1,1,1]
	v_pk_fma_f32 v[24:25], v[8:9], v[104:105], v[24:25] op_sel:[0,0,0] op_sel_hi:[0,1,1]
	v_pk_fma_f32 v[24:25], v[8:9], v[106:107], v[24:25] op_sel:[1,0,0] op_sel_hi:[1,1,1]
	v_pk_fma_f32 v[16:17], v[108:109], v[158:159], v[10:11] op_sel_hi:[1,0,1]
	v_pk_fma_f32 v[18:19], v[110:111], v[158:159], v[8:9] op_sel_hi:[1,0,1]
	v_add_f32_dpp v15, v24, v24 row_ror:8 row_mask:0xf bank_mask:0xf bound_ctrl:1
	v_add_f32_dpp v33, v25, v25 row_ror:8 row_mask:0xf bank_mask:0xf bound_ctrl:1
	ds_read_b128 v[76:79], v34 offset:12288
	v_add_f32_dpp v15, v15, v15 row_ror:4 row_mask:0xf bank_mask:0xf bound_ctrl:1
	ds_read_b128 v[80:83], v34 offset:12544
	ds_read_b128 v[84:87], v34 offset:12800
	v_add_f32_dpp v15, v15, v15 row_ror:2 row_mask:0xf bank_mask:0xf bound_ctrl:1
	ds_read_b128 v[88:91], v34 offset:13056
	s_nop 0
	v_add_f32_dpp v30, v15, v15 row_ror:1 row_mask:0xf bank_mask:0xf bound_ctrl:1
	ds_write2st64_b32 v37, v32, v33 offset0:16 offset1:18
	s_waitcnt lgkmcnt(5)
	v_pk_fma_f32 v[10:11], v[112:113], v[30:31], v[16:17] op_sel_hi:[1,0,1] neg_lo:[0,1,0] neg_hi:[0,1,0]
	v_pk_fma_f32 v[8:9], v[114:115], v[30:31], v[18:19] op_sel_hi:[1,0,1] neg_lo:[0,1,0] neg_hi:[0,1,0]
	v_pk_mul_f32 v[24:25], v[10:11], v[116:117] op_sel:[0,0] op_sel_hi:[0,1]
	v_pk_fma_f32 v[24:25], v[10:11], v[118:119], v[24:25] op_sel:[1,0,0] op_sel_hi:[1,1,1]
	v_pk_fma_f32 v[24:25], v[8:9], v[120:121], v[24:25] op_sel:[0,0,0] op_sel_hi:[0,1,1]
	v_pk_fma_f32 v[24:25], v[8:9], v[122:123], v[24:25] op_sel:[1,0,0] op_sel_hi:[1,1,1]
	v_pk_fma_f32 v[16:17], v[124:125], v[158:159], v[10:11] op_sel:[0,1,0] op_sel_hi:[1,1,1]
	v_pk_fma_f32 v[18:19], v[126:127], v[158:159], v[8:9] op_sel:[0,1,0] op_sel_hi:[1,1,1]
	v_add_f32_dpp v15, v24, v24 row_ror:8 row_mask:0xf bank_mask:0xf bound_ctrl:1
	v_add_f32_dpp v32, v25, v25 row_ror:8 row_mask:0xf bank_mask:0xf bound_ctrl:1
	ds_read_b128 v[92:95], v34 offset:13312
	v_add_f32_dpp v15, v15, v15 row_ror:4 row_mask:0xf bank_mask:0xf bound_ctrl:1
	ds_read_b128 v[96:99], v34 offset:13568
	ds_read_b128 v[100:103], v34 offset:13824
	v_add_f32_dpp v15, v15, v15 row_ror:2 row_mask:0xf bank_mask:0xf bound_ctrl:1
	ds_read_b128 v[104:107], v34 offset:14080
	s_nop 0
	v_add_f32_dpp v30, v15, v15 row_ror:1 row_mask:0xf bank_mask:0xf bound_ctrl:1
	s_waitcnt lgkmcnt(4)
	v_pk_fma_f32 v[10:11], v[128:129], v[30:31], v[16:17] op_sel_hi:[1,0,1] neg_lo:[0,1,0] neg_hi:[0,1,0]
	v_pk_fma_f32 v[8:9], v[130:131], v[30:31], v[18:19] op_sel_hi:[1,0,1] neg_lo:[0,1,0] neg_hi:[0,1,0]
	v_pk_mul_f32 v[24:25], v[10:11], v[132:133] op_sel:[0,0] op_sel_hi:[0,1]
	v_pk_fma_f32 v[24:25], v[10:11], v[134:135], v[24:25] op_sel:[1,0,0] op_sel_hi:[1,1,1]
	v_pk_fma_f32 v[24:25], v[8:9], v[136:137], v[24:25] op_sel:[0,0,0] op_sel_hi:[0,1,1]
	v_pk_fma_f32 v[24:25], v[8:9], v[138:139], v[24:25] op_sel:[1,0,0] op_sel_hi:[1,1,1]
	v_pk_fma_f32 v[16:17], v[76:77], v[160:161], v[10:11] op_sel_hi:[1,0,1]
	v_pk_fma_f32 v[18:19], v[78:79], v[160:161], v[8:9] op_sel_hi:[1,0,1]
	v_add_f32_dpp v15, v24, v24 row_ror:8 row_mask:0xf bank_mask:0xf bound_ctrl:1
	v_add_f32_dpp v33, v25, v25 row_ror:8 row_mask:0xf bank_mask:0xf bound_ctrl:1
	ds_read_b128 v[108:111], v34 offset:14336
	v_add_f32_dpp v15, v15, v15 row_ror:4 row_mask:0xf bank_mask:0xf bound_ctrl:1
	ds_read_b128 v[112:115], v34 offset:14592
	ds_read_b128 v[116:119], v34 offset:14848
	v_add_f32_dpp v15, v15, v15 row_ror:2 row_mask:0xf bank_mask:0xf bound_ctrl:1
	ds_read_b128 v[120:123], v34 offset:15104
	ds_read_b128 v[140:143], v34 offset:34048
	v_add_f32_dpp v30, v15, v15 row_ror:1 row_mask:0xf bank_mask:0xf bound_ctrl:1
	ds_write2st64_b32 v37, v32, v33 offset0:20 offset1:22
	s_waitcnt lgkmcnt(6)
	v_pk_fma_f32 v[10:11], v[80:81], v[30:31], v[16:17] op_sel_hi:[1,0,1] neg_lo:[0,1,0] neg_hi:[0,1,0]
	v_pk_fma_f32 v[8:9], v[82:83], v[30:31], v[18:19] op_sel_hi:[1,0,1] neg_lo:[0,1,0] neg_hi:[0,1,0]
	v_pk_mul_f32 v[24:25], v[10:11], v[84:85] op_sel:[0,0] op_sel_hi:[0,1]
	v_pk_fma_f32 v[24:25], v[10:11], v[86:87], v[24:25] op_sel:[1,0,0] op_sel_hi:[1,1,1]
	v_pk_fma_f32 v[24:25], v[8:9], v[88:89], v[24:25] op_sel:[0,0,0] op_sel_hi:[0,1,1]
	v_pk_fma_f32 v[24:25], v[8:9], v[90:91], v[24:25] op_sel:[1,0,0] op_sel_hi:[1,1,1]
	v_pk_fma_f32 v[16:17], v[92:93], v[160:161], v[10:11] op_sel:[0,1,0] op_sel_hi:[1,1,1]
	v_pk_fma_f32 v[18:19], v[94:95], v[160:161], v[8:9] op_sel:[0,1,0] op_sel_hi:[1,1,1]
	v_add_f32_dpp v15, v24, v24 row_ror:8 row_mask:0xf bank_mask:0xf bound_ctrl:1
	v_add_f32_dpp v32, v25, v25 row_ror:8 row_mask:0xf bank_mask:0xf bound_ctrl:1
	ds_read_b128 v[124:127], v34 offset:15360
	v_add_f32_dpp v15, v15, v15 row_ror:4 row_mask:0xf bank_mask:0xf bound_ctrl:1
	ds_read_b128 v[128:131], v34 offset:15616
	ds_read_b128 v[132:135], v34 offset:15872
	v_add_f32_dpp v15, v15, v15 row_ror:2 row_mask:0xf bank_mask:0xf bound_ctrl:1
	ds_read_b128 v[136:139], v34 offset:16128
	ds_read_b128 v[156:159], v35 offset:64
	v_add_f32_dpp v30, v15, v15 row_ror:1 row_mask:0xf bank_mask:0xf bound_ctrl:1
	s_waitcnt lgkmcnt(5)
	v_pk_fma_f32 v[10:11], v[96:97], v[30:31], v[16:17] op_sel_hi:[1,0,1] neg_lo:[0,1,0] neg_hi:[0,1,0]
	v_pk_fma_f32 v[8:9], v[98:99], v[30:31], v[18:19] op_sel_hi:[1,0,1] neg_lo:[0,1,0] neg_hi:[0,1,0]
	v_pk_mul_f32 v[24:25], v[10:11], v[100:101] op_sel:[0,0] op_sel_hi:[0,1]
	v_pk_fma_f32 v[24:25], v[10:11], v[102:103], v[24:25] op_sel:[1,0,0] op_sel_hi:[1,1,1]
	v_pk_fma_f32 v[24:25], v[8:9], v[104:105], v[24:25] op_sel:[0,0,0] op_sel_hi:[0,1,1]
	v_pk_fma_f32 v[24:25], v[8:9], v[106:107], v[24:25] op_sel:[1,0,0] op_sel_hi:[1,1,1]
	v_pk_fma_f32 v[16:17], v[108:109], v[162:163], v[10:11] op_sel_hi:[1,0,1]
	v_pk_fma_f32 v[18:19], v[110:111], v[162:163], v[8:9] op_sel_hi:[1,0,1]
	v_add_f32_dpp v15, v24, v24 row_ror:8 row_mask:0xf bank_mask:0xf bound_ctrl:1
	v_add_f32_dpp v33, v25, v25 row_ror:8 row_mask:0xf bank_mask:0xf bound_ctrl:1
	ds_read_b128 v[76:79], v34 offset:16384
	v_add_f32_dpp v15, v15, v15 row_ror:4 row_mask:0xf bank_mask:0xf bound_ctrl:1
	ds_read_b128 v[80:83], v34 offset:16640
	ds_read_b128 v[84:87], v34 offset:16896
	v_add_f32_dpp v15, v15, v15 row_ror:2 row_mask:0xf bank_mask:0xf bound_ctrl:1
	ds_read_b128 v[88:91], v34 offset:17152
	ds_read_b128 v[144:147], v34 offset:33280
	v_add_f32_dpp v30, v15, v15 row_ror:1 row_mask:0xf bank_mask:0xf bound_ctrl:1
	ds_write2st64_b32 v37, v32, v33 offset0:24 offset1:26
	s_waitcnt lgkmcnt(6)
	v_pk_fma_f32 v[10:11], v[112:113], v[30:31], v[16:17] op_sel_hi:[1,0,1] neg_lo:[0,1,0] neg_hi:[0,1,0]
	v_pk_fma_f32 v[8:9], v[114:115], v[30:31], v[18:19] op_sel_hi:[1,0,1] neg_lo:[0,1,0] neg_hi:[0,1,0]
	v_pk_mul_f32 v[24:25], v[10:11], v[116:117] op_sel:[0,0] op_sel_hi:[0,1]
	v_pk_fma_f32 v[24:25], v[10:11], v[118:119], v[24:25] op_sel:[1,0,0] op_sel_hi:[1,1,1]
	v_pk_fma_f32 v[24:25], v[8:9], v[120:121], v[24:25] op_sel:[0,0,0] op_sel_hi:[0,1,1]
	v_pk_fma_f32 v[24:25], v[8:9], v[122:123], v[24:25] op_sel:[1,0,0] op_sel_hi:[1,1,1]
	v_pk_fma_f32 v[16:17], v[124:125], v[162:163], v[10:11] op_sel:[0,1,0] op_sel_hi:[1,1,1]
	v_pk_fma_f32 v[18:19], v[126:127], v[162:163], v[8:9] op_sel:[0,1,0] op_sel_hi:[1,1,1]
	v_add_f32_dpp v15, v24, v24 row_ror:8 row_mask:0xf bank_mask:0xf bound_ctrl:1
	v_add_f32_dpp v32, v25, v25 row_ror:8 row_mask:0xf bank_mask:0xf bound_ctrl:1
	ds_read_b128 v[92:95], v34 offset:17408
	v_add_f32_dpp v15, v15, v15 row_ror:4 row_mask:0xf bank_mask:0xf bound_ctrl:1
	ds_read_b128 v[96:99], v34 offset:17664
	ds_read_b128 v[100:103], v34 offset:17920
	v_add_f32_dpp v15, v15, v15 row_ror:2 row_mask:0xf bank_mask:0xf bound_ctrl:1
	ds_read_b128 v[104:107], v34 offset:18176
	s_nop 0
	v_add_f32_dpp v30, v15, v15 row_ror:1 row_mask:0xf bank_mask:0xf bound_ctrl:1
	s_waitcnt lgkmcnt(4)
	v_pk_fma_f32 v[10:11], v[128:129], v[30:31], v[16:17] op_sel_hi:[1,0,1] neg_lo:[0,1,0] neg_hi:[0,1,0]
	v_pk_fma_f32 v[8:9], v[130:131], v[30:31], v[18:19] op_sel_hi:[1,0,1] neg_lo:[0,1,0] neg_hi:[0,1,0]
	v_pk_mul_f32 v[24:25], v[10:11], v[132:133] op_sel:[0,0] op_sel_hi:[0,1]
	v_pk_fma_f32 v[24:25], v[10:11], v[134:135], v[24:25] op_sel:[1,0,0] op_sel_hi:[1,1,1]
	v_pk_fma_f32 v[24:25], v[8:9], v[136:137], v[24:25] op_sel:[0,0,0] op_sel_hi:[0,1,1]
	v_pk_fma_f32 v[24:25], v[8:9], v[138:139], v[24:25] op_sel:[1,0,0] op_sel_hi:[1,1,1]
	s_nop 1
	v_add_f32_dpp v33, v25, v25 row_ror:8 row_mask:0xf bank_mask:0xf bound_ctrl:1
	ds_write2st64_b32 v37, v32, v33 offset0:28 offset1:30
	v_pk_mul_f32 v[10:11], v[10:11], v[140:141]
	v_pk_mul_f32 v[8:9], v[8:9], v[142:143]
	v_pk_mul_f32 v[24:25], v[10:11], v[144:145]
	v_pk_fma_f32 v[24:25], v[8:9], v[146:147], v[24:25]
	v_add_f32_e32 v24, v24, v25
	v_pk_fma_f32 v[16:17], v[76:77], v[156:157], v[10:11] op_sel_hi:[1,0,1]
	v_pk_fma_f32 v[18:19], v[78:79], v[156:157], v[8:9] op_sel_hi:[1,0,1]
	v_add_f32_dpp v15, v24, v24 row_ror:8 row_mask:0xf bank_mask:0xf bound_ctrl:1
	ds_read_b128 v[108:111], v34 offset:18432
	ds_read_b128 v[112:115], v34 offset:18688
	v_add_f32_dpp v15, v15, v15 row_ror:4 row_mask:0xf bank_mask:0xf bound_ctrl:1
	ds_read_b128 v[116:119], v34 offset:18944
	ds_read_b128 v[120:123], v34 offset:19200
	v_add_f32_dpp v15, v15, v15 row_ror:2 row_mask:0xf bank_mask:0xf bound_ctrl:1
	s_nop 1
	v_add_f32_dpp v30, v15, v15 row_ror:1 row_mask:0xf bank_mask:0xf bound_ctrl:1
	s_waitcnt lgkmcnt(5)
	v_pk_fma_f32 v[10:11], v[80:81], v[30:31], v[16:17] op_sel_hi:[1,0,1] neg_lo:[0,1,0] neg_hi:[0,1,0]
	v_pk_fma_f32 v[8:9], v[82:83], v[30:31], v[18:19] op_sel_hi:[1,0,1] neg_lo:[0,1,0] neg_hi:[0,1,0]
	v_pk_mul_f32 v[24:25], v[10:11], v[84:85] op_sel:[0,0] op_sel_hi:[0,1]
	v_pk_fma_f32 v[24:25], v[10:11], v[86:87], v[24:25] op_sel:[1,0,0] op_sel_hi:[1,1,1]
	v_pk_fma_f32 v[24:25], v[8:9], v[88:89], v[24:25] op_sel:[0,0,0] op_sel_hi:[0,1,1]
	v_pk_fma_f32 v[24:25], v[8:9], v[90:91], v[24:25] op_sel:[1,0,0] op_sel_hi:[1,1,1]
	v_pk_fma_f32 v[16:17], v[92:93], v[156:157], v[10:11] op_sel:[0,1,0] op_sel_hi:[1,1,1]
	v_pk_fma_f32 v[18:19], v[94:95], v[156:157], v[8:9] op_sel:[0,1,0] op_sel_hi:[1,1,1]
	v_add_f32_dpp v15, v24, v24 row_ror:8 row_mask:0xf bank_mask:0xf bound_ctrl:1
	v_add_f32_dpp v32, v25, v25 row_ror:8 row_mask:0xf bank_mask:0xf bound_ctrl:1
	ds_read_b128 v[124:127], v34 offset:19456
	v_add_f32_dpp v15, v15, v15 row_ror:4 row_mask:0xf bank_mask:0xf bound_ctrl:1
	ds_read_b128 v[128:131], v34 offset:19712
	ds_read_b128 v[132:135], v34 offset:19968
	v_add_f32_dpp v15, v15, v15 row_ror:2 row_mask:0xf bank_mask:0xf bound_ctrl:1
	ds_read_b128 v[136:139], v34 offset:20224
	ds_read_b128 v[160:163], v35 offset:80
	v_add_f32_dpp v30, v15, v15 row_ror:1 row_mask:0xf bank_mask:0xf bound_ctrl:1
	s_waitcnt lgkmcnt(5)
	v_pk_fma_f32 v[10:11], v[96:97], v[30:31], v[16:17] op_sel_hi:[1,0,1] neg_lo:[0,1,0] neg_hi:[0,1,0]
	v_pk_fma_f32 v[8:9], v[98:99], v[30:31], v[18:19] op_sel_hi:[1,0,1] neg_lo:[0,1,0] neg_hi:[0,1,0]
	v_pk_mul_f32 v[24:25], v[10:11], v[100:101] op_sel:[0,0] op_sel_hi:[0,1]
	v_pk_fma_f32 v[24:25], v[10:11], v[102:103], v[24:25] op_sel:[1,0,0] op_sel_hi:[1,1,1]
	v_pk_fma_f32 v[24:25], v[8:9], v[104:105], v[24:25] op_sel:[0,0,0] op_sel_hi:[0,1,1]
	v_pk_fma_f32 v[24:25], v[8:9], v[106:107], v[24:25] op_sel:[1,0,0] op_sel_hi:[1,1,1]
	v_pk_fma_f32 v[16:17], v[108:109], v[158:159], v[10:11] op_sel_hi:[1,0,1]
	v_pk_fma_f32 v[18:19], v[110:111], v[158:159], v[8:9] op_sel_hi:[1,0,1]
	v_add_f32_dpp v15, v24, v24 row_ror:8 row_mask:0xf bank_mask:0xf bound_ctrl:1
	v_add_f32_dpp v33, v25, v25 row_ror:8 row_mask:0xf bank_mask:0xf bound_ctrl:1
	ds_read_b128 v[76:79], v34 offset:20480
	v_add_f32_dpp v15, v15, v15 row_ror:4 row_mask:0xf bank_mask:0xf bound_ctrl:1
	ds_read_b128 v[80:83], v34 offset:20736
	ds_read_b128 v[84:87], v34 offset:20992
	v_add_f32_dpp v15, v15, v15 row_ror:2 row_mask:0xf bank_mask:0xf bound_ctrl:1
	ds_read_b128 v[88:91], v34 offset:21248
	s_nop 0
	v_add_f32_dpp v30, v15, v15 row_ror:1 row_mask:0xf bank_mask:0xf bound_ctrl:1
	ds_write2st64_b32 v37, v32, v33 offset0:32 offset1:34
	s_waitcnt lgkmcnt(5)
	v_pk_fma_f32 v[10:11], v[112:113], v[30:31], v[16:17] op_sel_hi:[1,0,1] neg_lo:[0,1,0] neg_hi:[0,1,0]
	v_pk_fma_f32 v[8:9], v[114:115], v[30:31], v[18:19] op_sel_hi:[1,0,1] neg_lo:[0,1,0] neg_hi:[0,1,0]
	v_pk_mul_f32 v[24:25], v[10:11], v[116:117] op_sel:[0,0] op_sel_hi:[0,1]
	v_pk_fma_f32 v[24:25], v[10:11], v[118:119], v[24:25] op_sel:[1,0,0] op_sel_hi:[1,1,1]
	v_pk_fma_f32 v[24:25], v[8:9], v[120:121], v[24:25] op_sel:[0,0,0] op_sel_hi:[0,1,1]
	v_pk_fma_f32 v[24:25], v[8:9], v[122:123], v[24:25] op_sel:[1,0,0] op_sel_hi:[1,1,1]
	v_pk_fma_f32 v[16:17], v[124:125], v[158:159], v[10:11] op_sel:[0,1,0] op_sel_hi:[1,1,1]
	v_pk_fma_f32 v[18:19], v[126:127], v[158:159], v[8:9] op_sel:[0,1,0] op_sel_hi:[1,1,1]
	v_add_f32_dpp v15, v24, v24 row_ror:8 row_mask:0xf bank_mask:0xf bound_ctrl:1
	v_add_f32_dpp v32, v25, v25 row_ror:8 row_mask:0xf bank_mask:0xf bound_ctrl:1
	ds_read_b128 v[92:95], v34 offset:21504
	v_add_f32_dpp v15, v15, v15 row_ror:4 row_mask:0xf bank_mask:0xf bound_ctrl:1
	ds_read_b128 v[96:99], v34 offset:21760
	ds_read_b128 v[100:103], v34 offset:22016
	v_add_f32_dpp v15, v15, v15 row_ror:2 row_mask:0xf bank_mask:0xf bound_ctrl:1
	ds_read_b128 v[104:107], v34 offset:22272
	s_nop 0
	v_add_f32_dpp v30, v15, v15 row_ror:1 row_mask:0xf bank_mask:0xf bound_ctrl:1
	s_waitcnt lgkmcnt(4)
	v_pk_fma_f32 v[10:11], v[128:129], v[30:31], v[16:17] op_sel_hi:[1,0,1] neg_lo:[0,1,0] neg_hi:[0,1,0]
	v_pk_fma_f32 v[8:9], v[130:131], v[30:31], v[18:19] op_sel_hi:[1,0,1] neg_lo:[0,1,0] neg_hi:[0,1,0]
	v_pk_mul_f32 v[24:25], v[10:11], v[132:133] op_sel:[0,0] op_sel_hi:[0,1]
	v_pk_fma_f32 v[24:25], v[10:11], v[134:135], v[24:25] op_sel:[1,0,0] op_sel_hi:[1,1,1]
	v_pk_fma_f32 v[24:25], v[8:9], v[136:137], v[24:25] op_sel:[0,0,0] op_sel_hi:[0,1,1]
	v_pk_fma_f32 v[24:25], v[8:9], v[138:139], v[24:25] op_sel:[1,0,0] op_sel_hi:[1,1,1]
	v_pk_fma_f32 v[16:17], v[76:77], v[160:161], v[10:11] op_sel_hi:[1,0,1]
	v_pk_fma_f32 v[18:19], v[78:79], v[160:161], v[8:9] op_sel_hi:[1,0,1]
	v_add_f32_dpp v15, v24, v24 row_ror:8 row_mask:0xf bank_mask:0xf bound_ctrl:1
	v_add_f32_dpp v33, v25, v25 row_ror:8 row_mask:0xf bank_mask:0xf bound_ctrl:1
	ds_read_b128 v[108:111], v34 offset:22528
	v_add_f32_dpp v15, v15, v15 row_ror:4 row_mask:0xf bank_mask:0xf bound_ctrl:1
	ds_read_b128 v[112:115], v34 offset:22784
	ds_read_b128 v[116:119], v34 offset:23040
	v_add_f32_dpp v15, v15, v15 row_ror:2 row_mask:0xf bank_mask:0xf bound_ctrl:1
	ds_read_b128 v[120:123], v34 offset:23296
	ds_read_b128 v[140:143], v34 offset:34304
	v_add_f32_dpp v30, v15, v15 row_ror:1 row_mask:0xf bank_mask:0xf bound_ctrl:1
	ds_write2st64_b32 v37, v32, v33 offset0:36 offset1:38
	s_waitcnt lgkmcnt(6)
	v_pk_fma_f32 v[10:11], v[80:81], v[30:31], v[16:17] op_sel_hi:[1,0,1] neg_lo:[0,1,0] neg_hi:[0,1,0]
	v_pk_fma_f32 v[8:9], v[82:83], v[30:31], v[18:19] op_sel_hi:[1,0,1] neg_lo:[0,1,0] neg_hi:[0,1,0]
	v_pk_mul_f32 v[24:25], v[10:11], v[84:85] op_sel:[0,0] op_sel_hi:[0,1]
	v_pk_fma_f32 v[24:25], v[10:11], v[86:87], v[24:25] op_sel:[1,0,0] op_sel_hi:[1,1,1]
	v_pk_fma_f32 v[24:25], v[8:9], v[88:89], v[24:25] op_sel:[0,0,0] op_sel_hi:[0,1,1]
	v_pk_fma_f32 v[24:25], v[8:9], v[90:91], v[24:25] op_sel:[1,0,0] op_sel_hi:[1,1,1]
	v_pk_fma_f32 v[16:17], v[92:93], v[160:161], v[10:11] op_sel:[0,1,0] op_sel_hi:[1,1,1]
	v_pk_fma_f32 v[18:19], v[94:95], v[160:161], v[8:9] op_sel:[0,1,0] op_sel_hi:[1,1,1]
	v_add_f32_dpp v15, v24, v24 row_ror:8 row_mask:0xf bank_mask:0xf bound_ctrl:1
	v_add_f32_dpp v32, v25, v25 row_ror:8 row_mask:0xf bank_mask:0xf bound_ctrl:1
	ds_read_b128 v[124:127], v34 offset:23552
	v_add_f32_dpp v15, v15, v15 row_ror:4 row_mask:0xf bank_mask:0xf bound_ctrl:1
	ds_read_b128 v[128:131], v34 offset:23808
	ds_read_b128 v[132:135], v34 offset:24064
	v_add_f32_dpp v15, v15, v15 row_ror:2 row_mask:0xf bank_mask:0xf bound_ctrl:1
	ds_read_b128 v[136:139], v34 offset:24320
	ds_read_b128 v[156:159], v35 offset:96
	v_add_f32_dpp v30, v15, v15 row_ror:1 row_mask:0xf bank_mask:0xf bound_ctrl:1
	s_waitcnt lgkmcnt(5)
	v_pk_fma_f32 v[10:11], v[96:97], v[30:31], v[16:17] op_sel_hi:[1,0,1] neg_lo:[0,1,0] neg_hi:[0,1,0]
	v_pk_fma_f32 v[8:9], v[98:99], v[30:31], v[18:19] op_sel_hi:[1,0,1] neg_lo:[0,1,0] neg_hi:[0,1,0]
	v_pk_mul_f32 v[24:25], v[10:11], v[100:101] op_sel:[0,0] op_sel_hi:[0,1]
	v_pk_fma_f32 v[24:25], v[10:11], v[102:103], v[24:25] op_sel:[1,0,0] op_sel_hi:[1,1,1]
	v_pk_fma_f32 v[24:25], v[8:9], v[104:105], v[24:25] op_sel:[0,0,0] op_sel_hi:[0,1,1]
	v_pk_fma_f32 v[24:25], v[8:9], v[106:107], v[24:25] op_sel:[1,0,0] op_sel_hi:[1,1,1]
	v_pk_fma_f32 v[16:17], v[108:109], v[162:163], v[10:11] op_sel_hi:[1,0,1]
	v_pk_fma_f32 v[18:19], v[110:111], v[162:163], v[8:9] op_sel_hi:[1,0,1]
	v_add_f32_dpp v15, v24, v24 row_ror:8 row_mask:0xf bank_mask:0xf bound_ctrl:1
	v_add_f32_dpp v33, v25, v25 row_ror:8 row_mask:0xf bank_mask:0xf bound_ctrl:1
	ds_read_b128 v[76:79], v34 offset:24576
	v_add_f32_dpp v15, v15, v15 row_ror:4 row_mask:0xf bank_mask:0xf bound_ctrl:1
	ds_read_b128 v[80:83], v34 offset:24832
	ds_read_b128 v[84:87], v34 offset:25088
	v_add_f32_dpp v15, v15, v15 row_ror:2 row_mask:0xf bank_mask:0xf bound_ctrl:1
	ds_read_b128 v[88:91], v34 offset:25344
	ds_read_b128 v[144:147], v34 offset:33536
	v_add_f32_dpp v30, v15, v15 row_ror:1 row_mask:0xf bank_mask:0xf bound_ctrl:1
	ds_write2st64_b32 v37, v32, v33 offset0:40 offset1:42
	s_waitcnt lgkmcnt(6)
	v_pk_fma_f32 v[10:11], v[112:113], v[30:31], v[16:17] op_sel_hi:[1,0,1] neg_lo:[0,1,0] neg_hi:[0,1,0]
	v_pk_fma_f32 v[8:9], v[114:115], v[30:31], v[18:19] op_sel_hi:[1,0,1] neg_lo:[0,1,0] neg_hi:[0,1,0]
	v_pk_mul_f32 v[24:25], v[10:11], v[116:117] op_sel:[0,0] op_sel_hi:[0,1]
	v_pk_fma_f32 v[24:25], v[10:11], v[118:119], v[24:25] op_sel:[1,0,0] op_sel_hi:[1,1,1]
	v_pk_fma_f32 v[24:25], v[8:9], v[120:121], v[24:25] op_sel:[0,0,0] op_sel_hi:[0,1,1]
	v_pk_fma_f32 v[24:25], v[8:9], v[122:123], v[24:25] op_sel:[1,0,0] op_sel_hi:[1,1,1]
	v_pk_fma_f32 v[16:17], v[124:125], v[162:163], v[10:11] op_sel:[0,1,0] op_sel_hi:[1,1,1]
	v_pk_fma_f32 v[18:19], v[126:127], v[162:163], v[8:9] op_sel:[0,1,0] op_sel_hi:[1,1,1]
	v_add_f32_dpp v15, v24, v24 row_ror:8 row_mask:0xf bank_mask:0xf bound_ctrl:1
	v_add_f32_dpp v32, v25, v25 row_ror:8 row_mask:0xf bank_mask:0xf bound_ctrl:1
	ds_read_b128 v[92:95], v34 offset:25600
	v_add_f32_dpp v15, v15, v15 row_ror:4 row_mask:0xf bank_mask:0xf bound_ctrl:1
	ds_read_b128 v[96:99], v34 offset:25856
	ds_read_b128 v[100:103], v34 offset:26112
	v_add_f32_dpp v15, v15, v15 row_ror:2 row_mask:0xf bank_mask:0xf bound_ctrl:1
	ds_read_b128 v[104:107], v34 offset:26368
	s_nop 0
	v_add_f32_dpp v30, v15, v15 row_ror:1 row_mask:0xf bank_mask:0xf bound_ctrl:1
	s_waitcnt lgkmcnt(4)
	v_pk_fma_f32 v[10:11], v[128:129], v[30:31], v[16:17] op_sel_hi:[1,0,1] neg_lo:[0,1,0] neg_hi:[0,1,0]
	v_pk_fma_f32 v[8:9], v[130:131], v[30:31], v[18:19] op_sel_hi:[1,0,1] neg_lo:[0,1,0] neg_hi:[0,1,0]
	v_pk_mul_f32 v[24:25], v[10:11], v[132:133] op_sel:[0,0] op_sel_hi:[0,1]
	v_pk_fma_f32 v[24:25], v[10:11], v[134:135], v[24:25] op_sel:[1,0,0] op_sel_hi:[1,1,1]
	v_pk_fma_f32 v[24:25], v[8:9], v[136:137], v[24:25] op_sel:[0,0,0] op_sel_hi:[0,1,1]
	v_pk_fma_f32 v[24:25], v[8:9], v[138:139], v[24:25] op_sel:[1,0,0] op_sel_hi:[1,1,1]
	s_nop 1
	v_add_f32_dpp v33, v25, v25 row_ror:8 row_mask:0xf bank_mask:0xf bound_ctrl:1
	ds_write2st64_b32 v37, v32, v33 offset0:44 offset1:46
	v_pk_mul_f32 v[10:11], v[10:11], v[140:141]
	v_pk_mul_f32 v[8:9], v[8:9], v[142:143]
	v_pk_mul_f32 v[24:25], v[10:11], v[144:145]
	v_pk_fma_f32 v[24:25], v[8:9], v[146:147], v[24:25]
	v_add_f32_e32 v24, v24, v25
	v_pk_fma_f32 v[16:17], v[76:77], v[156:157], v[10:11] op_sel_hi:[1,0,1]
	v_pk_fma_f32 v[18:19], v[78:79], v[156:157], v[8:9] op_sel_hi:[1,0,1]
	v_add_f32_dpp v15, v24, v24 row_ror:8 row_mask:0xf bank_mask:0xf bound_ctrl:1
	ds_read_b128 v[108:111], v34 offset:26624
	ds_read_b128 v[112:115], v34 offset:26880
	v_add_f32_dpp v15, v15, v15 row_ror:4 row_mask:0xf bank_mask:0xf bound_ctrl:1
	ds_read_b128 v[116:119], v34 offset:27136
	ds_read_b128 v[120:123], v34 offset:27392
	v_add_f32_dpp v15, v15, v15 row_ror:2 row_mask:0xf bank_mask:0xf bound_ctrl:1
	s_nop 1
	v_add_f32_dpp v30, v15, v15 row_ror:1 row_mask:0xf bank_mask:0xf bound_ctrl:1
	s_waitcnt lgkmcnt(5)
	v_pk_fma_f32 v[10:11], v[80:81], v[30:31], v[16:17] op_sel_hi:[1,0,1] neg_lo:[0,1,0] neg_hi:[0,1,0]
	v_pk_fma_f32 v[8:9], v[82:83], v[30:31], v[18:19] op_sel_hi:[1,0,1] neg_lo:[0,1,0] neg_hi:[0,1,0]
	v_pk_mul_f32 v[24:25], v[10:11], v[84:85] op_sel:[0,0] op_sel_hi:[0,1]
	v_pk_fma_f32 v[24:25], v[10:11], v[86:87], v[24:25] op_sel:[1,0,0] op_sel_hi:[1,1,1]
	v_pk_fma_f32 v[24:25], v[8:9], v[88:89], v[24:25] op_sel:[0,0,0] op_sel_hi:[0,1,1]
	v_pk_fma_f32 v[24:25], v[8:9], v[90:91], v[24:25] op_sel:[1,0,0] op_sel_hi:[1,1,1]
	v_pk_fma_f32 v[16:17], v[92:93], v[156:157], v[10:11] op_sel:[0,1,0] op_sel_hi:[1,1,1]
	v_pk_fma_f32 v[18:19], v[94:95], v[156:157], v[8:9] op_sel:[0,1,0] op_sel_hi:[1,1,1]
	v_add_f32_dpp v15, v24, v24 row_ror:8 row_mask:0xf bank_mask:0xf bound_ctrl:1
	v_add_f32_dpp v32, v25, v25 row_ror:8 row_mask:0xf bank_mask:0xf bound_ctrl:1
	ds_read_b128 v[124:127], v34 offset:27648
	v_add_f32_dpp v15, v15, v15 row_ror:4 row_mask:0xf bank_mask:0xf bound_ctrl:1
	ds_read_b128 v[128:131], v34 offset:27904
	ds_read_b128 v[132:135], v34 offset:28160
	v_add_f32_dpp v15, v15, v15 row_ror:2 row_mask:0xf bank_mask:0xf bound_ctrl:1
	ds_read_b128 v[136:139], v34 offset:28416
	ds_read_b128 v[160:163], v35 offset:112
	v_add_f32_dpp v30, v15, v15 row_ror:1 row_mask:0xf bank_mask:0xf bound_ctrl:1
	s_waitcnt lgkmcnt(5)
	v_pk_fma_f32 v[10:11], v[96:97], v[30:31], v[16:17] op_sel_hi:[1,0,1] neg_lo:[0,1,0] neg_hi:[0,1,0]
	v_pk_fma_f32 v[8:9], v[98:99], v[30:31], v[18:19] op_sel_hi:[1,0,1] neg_lo:[0,1,0] neg_hi:[0,1,0]
	v_pk_mul_f32 v[24:25], v[10:11], v[100:101] op_sel:[0,0] op_sel_hi:[0,1]
	v_pk_fma_f32 v[24:25], v[10:11], v[102:103], v[24:25] op_sel:[1,0,0] op_sel_hi:[1,1,1]
	v_pk_fma_f32 v[24:25], v[8:9], v[104:105], v[24:25] op_sel:[0,0,0] op_sel_hi:[0,1,1]
	v_pk_fma_f32 v[24:25], v[8:9], v[106:107], v[24:25] op_sel:[1,0,0] op_sel_hi:[1,1,1]
	v_pk_fma_f32 v[16:17], v[108:109], v[158:159], v[10:11] op_sel_hi:[1,0,1]
	v_pk_fma_f32 v[18:19], v[110:111], v[158:159], v[8:9] op_sel_hi:[1,0,1]
	v_add_f32_dpp v15, v24, v24 row_ror:8 row_mask:0xf bank_mask:0xf bound_ctrl:1
	v_add_f32_dpp v33, v25, v25 row_ror:8 row_mask:0xf bank_mask:0xf bound_ctrl:1
	ds_read_b128 v[76:79], v34 offset:28672
	v_add_f32_dpp v15, v15, v15 row_ror:4 row_mask:0xf bank_mask:0xf bound_ctrl:1
	ds_read_b128 v[80:83], v34 offset:28928
	ds_read_b128 v[84:87], v34 offset:29184
	v_add_f32_dpp v15, v15, v15 row_ror:2 row_mask:0xf bank_mask:0xf bound_ctrl:1
	ds_read_b128 v[88:91], v34 offset:29440
	s_nop 0
	v_add_f32_dpp v30, v15, v15 row_ror:1 row_mask:0xf bank_mask:0xf bound_ctrl:1
	ds_write2st64_b32 v37, v32, v33 offset0:48 offset1:50
	ds_read_b128 v[56:59], v52
	s_waitcnt lgkmcnt(5)
	v_pk_fma_f32 v[10:11], v[112:113], v[30:31], v[16:17] op_sel_hi:[1,0,1] neg_lo:[0,1,0] neg_hi:[0,1,0]
	v_pk_fma_f32 v[8:9], v[114:115], v[30:31], v[18:19] op_sel_hi:[1,0,1] neg_lo:[0,1,0] neg_hi:[0,1,0]
	v_pk_mul_f32 v[24:25], v[10:11], v[116:117] op_sel:[0,0] op_sel_hi:[0,1]
	v_pk_fma_f32 v[24:25], v[10:11], v[118:119], v[24:25] op_sel:[1,0,0] op_sel_hi:[1,1,1]
	v_pk_fma_f32 v[24:25], v[8:9], v[120:121], v[24:25] op_sel:[0,0,0] op_sel_hi:[0,1,1]
	v_pk_fma_f32 v[24:25], v[8:9], v[122:123], v[24:25] op_sel:[1,0,0] op_sel_hi:[1,1,1]
	v_pk_fma_f32 v[16:17], v[124:125], v[158:159], v[10:11] op_sel:[0,1,0] op_sel_hi:[1,1,1]
	v_pk_fma_f32 v[18:19], v[126:127], v[158:159], v[8:9] op_sel:[0,1,0] op_sel_hi:[1,1,1]
	v_add_f32_dpp v15, v24, v24 row_ror:8 row_mask:0xf bank_mask:0xf bound_ctrl:1
	v_add_f32_dpp v32, v25, v25 row_ror:8 row_mask:0xf bank_mask:0xf bound_ctrl:1
	ds_read_b128 v[92:95], v34 offset:29696
	v_add_f32_dpp v15, v15, v15 row_ror:4 row_mask:0xf bank_mask:0xf bound_ctrl:1
	ds_read_b128 v[96:99], v34 offset:29952
	ds_read_b128 v[100:103], v34 offset:30208
	v_add_f32_dpp v15, v15, v15 row_ror:2 row_mask:0xf bank_mask:0xf bound_ctrl:1
	ds_read_b128 v[104:107], v34 offset:30464
	s_nop 0
	v_add_f32_dpp v30, v15, v15 row_ror:1 row_mask:0xf bank_mask:0xf bound_ctrl:1
	s_waitcnt lgkmcnt(4)
	v_min_u32_e32 v56, v56, v57
	v_min3_u32 v56, v56, v58, v59
	v_pk_fma_f32 v[10:11], v[128:129], v[30:31], v[16:17] op_sel_hi:[1,0,1] neg_lo:[0,1,0] neg_hi:[0,1,0]
	v_pk_fma_f32 v[8:9], v[130:131], v[30:31], v[18:19] op_sel_hi:[1,0,1] neg_lo:[0,1,0] neg_hi:[0,1,0]
	v_pk_mul_f32 v[24:25], v[10:11], v[132:133] op_sel:[0,0] op_sel_hi:[0,1]
	v_pk_fma_f32 v[24:25], v[10:11], v[134:135], v[24:25] op_sel:[1,0,0] op_sel_hi:[1,1,1]
	v_pk_fma_f32 v[24:25], v[8:9], v[136:137], v[24:25] op_sel:[0,0,0] op_sel_hi:[0,1,1]
	v_pk_fma_f32 v[24:25], v[8:9], v[138:139], v[24:25] op_sel:[1,0,0] op_sel_hi:[1,1,1]
	v_pk_fma_f32 v[16:17], v[76:77], v[160:161], v[10:11] op_sel_hi:[1,0,1]
	v_pk_fma_f32 v[18:19], v[78:79], v[160:161], v[8:9] op_sel_hi:[1,0,1]
	v_add_f32_dpp v15, v24, v24 row_ror:8 row_mask:0xf bank_mask:0xf bound_ctrl:1
	v_add_f32_dpp v33, v25, v25 row_ror:8 row_mask:0xf bank_mask:0xf bound_ctrl:1
	ds_read_b128 v[108:111], v34 offset:30720
	v_add_f32_dpp v15, v15, v15 row_ror:4 row_mask:0xf bank_mask:0xf bound_ctrl:1
	ds_read_b128 v[112:115], v34 offset:30976
	ds_read_b128 v[116:119], v34 offset:31232
	v_add_f32_dpp v15, v15, v15 row_ror:2 row_mask:0xf bank_mask:0xf bound_ctrl:1
	ds_read_b128 v[120:123], v34 offset:31488
	ds_read_b128 v[140:143], v34 offset:34560
	v_add_f32_dpp v30, v15, v15 row_ror:1 row_mask:0xf bank_mask:0xf bound_ctrl:1
	ds_write2st64_b32 v37, v32, v33 offset0:52 offset1:54
	s_waitcnt lgkmcnt(6)
	v_pk_fma_f32 v[10:11], v[80:81], v[30:31], v[16:17] op_sel_hi:[1,0,1] neg_lo:[0,1,0] neg_hi:[0,1,0]
	v_pk_fma_f32 v[8:9], v[82:83], v[30:31], v[18:19] op_sel_hi:[1,0,1] neg_lo:[0,1,0] neg_hi:[0,1,0]
	v_pk_mul_f32 v[24:25], v[10:11], v[84:85] op_sel:[0,0] op_sel_hi:[0,1]
	v_pk_fma_f32 v[24:25], v[10:11], v[86:87], v[24:25] op_sel:[1,0,0] op_sel_hi:[1,1,1]
	v_pk_fma_f32 v[24:25], v[8:9], v[88:89], v[24:25] op_sel:[0,0,0] op_sel_hi:[0,1,1]
	v_pk_fma_f32 v[24:25], v[8:9], v[90:91], v[24:25] op_sel:[1,0,0] op_sel_hi:[1,1,1]
	v_pk_fma_f32 v[16:17], v[92:93], v[160:161], v[10:11] op_sel:[0,1,0] op_sel_hi:[1,1,1]
	v_pk_fma_f32 v[18:19], v[94:95], v[160:161], v[8:9] op_sel:[0,1,0] op_sel_hi:[1,1,1]
	v_add_f32_dpp v15, v24, v24 row_ror:8 row_mask:0xf bank_mask:0xf bound_ctrl:1
	v_add_f32_dpp v32, v25, v25 row_ror:8 row_mask:0xf bank_mask:0xf bound_ctrl:1
	ds_read_b128 v[124:127], v34 offset:31744
	v_add_f32_dpp v15, v15, v15 row_ror:4 row_mask:0xf bank_mask:0xf bound_ctrl:1
	ds_read_b128 v[128:131], v34 offset:32000
	ds_read_b128 v[132:135], v34 offset:32256
	v_add_f32_dpp v15, v15, v15 row_ror:2 row_mask:0xf bank_mask:0xf bound_ctrl:1
	ds_read_b128 v[136:139], v34 offset:32512
	s_nop 0
	v_add_f32_dpp v30, v15, v15 row_ror:1 row_mask:0xf bank_mask:0xf bound_ctrl:1
	v_readfirstlane_b32 s54, v56
	s_add_u32 s64, s6, 2
	s_cmp_lt_u32 s54, s64
	s_cbranch_scc1 .Lss_spin_0
.Lss_ok_0:
	s_waitcnt lgkmcnt(4)
	v_pk_fma_f32 v[10:11], v[96:97], v[30:31], v[16:17] op_sel_hi:[1,0,1] neg_lo:[0,1,0] neg_hi:[0,1,0]
	v_pk_fma_f32 v[8:9], v[98:99], v[30:31], v[18:19] op_sel_hi:[1,0,1] neg_lo:[0,1,0] neg_hi:[0,1,0]
	v_pk_mul_f32 v[24:25], v[10:11], v[100:101] op_sel:[0,0] op_sel_hi:[0,1]
	v_pk_fma_f32 v[24:25], v[10:11], v[102:103], v[24:25] op_sel:[1,0,0] op_sel_hi:[1,1,1]
	v_pk_fma_f32 v[24:25], v[8:9], v[104:105], v[24:25] op_sel:[0,0,0] op_sel_hi:[0,1,1]
	v_pk_fma_f32 v[24:25], v[8:9], v[106:107], v[24:25] op_sel:[1,0,0] op_sel_hi:[1,1,1]
	v_pk_fma_f32 v[16:17], v[108:109], v[162:163], v[10:11] op_sel_hi:[1,0,1]
	v_pk_fma_f32 v[18:19], v[110:111], v[162:163], v[8:9] op_sel_hi:[1,0,1]
	v_add_f32_dpp v15, v24, v24 row_ror:8 row_mask:0xf bank_mask:0xf bound_ctrl:1
	v_add_f32_dpp v33, v25, v25 row_ror:8 row_mask:0xf bank_mask:0xf bound_ctrl:1
	ds_read_b128 v[76:79], v48 offset:0
	v_add_f32_dpp v15, v15, v15 row_ror:4 row_mask:0xf bank_mask:0xf bound_ctrl:1
	ds_read_b128 v[80:83], v48 offset:256
	ds_read_b128 v[84:87], v48 offset:512
	v_add_f32_dpp v15, v15, v15 row_ror:2 row_mask:0xf bank_mask:0xf bound_ctrl:1
	ds_read_b128 v[88:91], v48 offset:768
	ds_read_b128 v[144:147], v48 offset:32768
	v_add_f32_dpp v30, v15, v15 row_ror:1 row_mask:0xf bank_mask:0xf bound_ctrl:1
	ds_write2st64_b32 v37, v32, v33 offset0:56 offset1:58
	ds_read_b128 v[156:159], v49 offset:0
	s_waitcnt lgkmcnt(7)
	v_pk_fma_f32 v[10:11], v[112:113], v[30:31], v[16:17] op_sel_hi:[1,0,1] neg_lo:[0,1,0] neg_hi:[0,1,0]
	v_pk_fma_f32 v[8:9], v[114:115], v[30:31], v[18:19] op_sel_hi:[1,0,1] neg_lo:[0,1,0] neg_hi:[0,1,0]
	v_pk_mul_f32 v[24:25], v[10:11], v[116:117] op_sel:[0,0] op_sel_hi:[0,1]
	v_pk_fma_f32 v[24:25], v[10:11], v[118:119], v[24:25] op_sel:[1,0,0] op_sel_hi:[1,1,1]
	v_pk_fma_f32 v[24:25], v[8:9], v[120:121], v[24:25] op_sel:[0,0,0] op_sel_hi:[0,1,1]
	v_pk_fma_f32 v[24:25], v[8:9], v[122:123], v[24:25] op_sel:[1,0,0] op_sel_hi:[1,1,1]
	v_pk_fma_f32 v[16:17], v[124:125], v[162:163], v[10:11] op_sel:[0,1,0] op_sel_hi:[1,1,1]
	v_pk_fma_f32 v[18:19], v[126:127], v[162:163], v[8:9] op_sel:[0,1,0] op_sel_hi:[1,1,1]
	v_add_f32_dpp v15, v24, v24 row_ror:8 row_mask:0xf bank_mask:0xf bound_ctrl:1
	v_add_f32_dpp v32, v25, v25 row_ror:8 row_mask:0xf bank_mask:0xf bound_ctrl:1
	ds_read_b128 v[92:95], v48 offset:1024
	v_add_f32_dpp v15, v15, v15 row_ror:4 row_mask:0xf bank_mask:0xf bound_ctrl:1
	ds_read_b128 v[96:99], v48 offset:1280
	ds_read_b128 v[100:103], v48 offset:1536
	v_add_f32_dpp v15, v15, v15 row_ror:2 row_mask:0xf bank_mask:0xf bound_ctrl:1
	ds_read_b128 v[104:107], v48 offset:1792
	s_nop 0
	v_add_f32_dpp v30, v15, v15 row_ror:1 row_mask:0xf bank_mask:0xf bound_ctrl:1
	s_waitcnt lgkmcnt(4)
	v_pk_fma_f32 v[10:11], v[128:129], v[30:31], v[16:17] op_sel_hi:[1,0,1] neg_lo:[0,1,0] neg_hi:[0,1,0]
	v_pk_fma_f32 v[8:9], v[130:131], v[30:31], v[18:19] op_sel_hi:[1,0,1] neg_lo:[0,1,0] neg_hi:[0,1,0]
	v_pk_mul_f32 v[24:25], v[10:11], v[132:133] op_sel:[0,0] op_sel_hi:[0,1]
	v_pk_fma_f32 v[24:25], v[10:11], v[134:135], v[24:25] op_sel:[1,0,0] op_sel_hi:[1,1,1]
	v_pk_fma_f32 v[24:25], v[8:9], v[136:137], v[24:25] op_sel:[0,0,0] op_sel_hi:[0,1,1]
	v_pk_fma_f32 v[24:25], v[8:9], v[138:139], v[24:25] op_sel:[1,0,0] op_sel_hi:[1,1,1]
	s_nop 1
	v_add_f32_dpp v33, v25, v25 row_ror:8 row_mask:0xf bank_mask:0xf bound_ctrl:1
	ds_write2st64_b32 v37, v32, v33 offset0:60 offset1:62
	v_pk_mul_f32 v[10:11], v[10:11], v[140:141]
	v_pk_mul_f32 v[8:9], v[8:9], v[142:143]
	v_pk_mul_f32 v[24:25], v[10:11], v[144:145]
	v_pk_fma_f32 v[24:25], v[8:9], v[146:147], v[24:25]
	v_add_f32_e32 v24, v24, v25
	v_pk_fma_f32 v[16:17], v[76:77], v[156:157], v[10:11] op_sel_hi:[1,0,1]
	v_pk_fma_f32 v[18:19], v[78:79], v[156:157], v[8:9] op_sel_hi:[1,0,1]
	v_add_f32_dpp v15, v24, v24 row_ror:8 row_mask:0xf bank_mask:0xf bound_ctrl:1
	v_add_u32_e32 v51, 1, v51
	s_add_u32 s6, s6, 1
	v_add_f32_dpp v15, v15, v15 row_ror:4 row_mask:0xf bank_mask:0xf bound_ctrl:1
	ds_write_b32 v53, v51
	ds_read_b128 v[108:111], v48 offset:2048
	v_add_f32_dpp v15, v15, v15 row_ror:2 row_mask:0xf bank_mask:0xf bound_ctrl:1
	ds_read_b128 v[112:115], v48 offset:2304
	ds_read_b128 v[116:119], v48 offset:2560
	v_add_f32_dpp v30, v15, v15 row_ror:1 row_mask:0xf bank_mask:0xf bound_ctrl:1
	ds_read_b128 v[120:123], v48 offset:2816
	s_waitcnt lgkmcnt(6)
	v_pk_fma_f32 v[10:11], v[80:81], v[30:31], v[16:17] op_sel_hi:[1,0,1] neg_lo:[0,1,0] neg_hi:[0,1,0]
	v_pk_fma_f32 v[8:9], v[82:83], v[30:31], v[18:19] op_sel_hi:[1,0,1] neg_lo:[0,1,0] neg_hi:[0,1,0]
	v_pk_mul_f32 v[24:25], v[10:11], v[84:85] op_sel:[0,0] op_sel_hi:[0,1]
	v_pk_fma_f32 v[24:25], v[10:11], v[86:87], v[24:25] op_sel:[1,0,0] op_sel_hi:[1,1,1]
	v_pk_fma_f32 v[24:25], v[8:9], v[88:89], v[24:25] op_sel:[0,0,0] op_sel_hi:[0,1,1]
	v_pk_fma_f32 v[24:25], v[8:9], v[90:91], v[24:25] op_sel:[1,0,0] op_sel_hi:[1,1,1]
	v_pk_fma_f32 v[16:17], v[92:93], v[156:157], v[10:11] op_sel:[0,1,0] op_sel_hi:[1,1,1]
	v_pk_fma_f32 v[18:19], v[94:95], v[156:157], v[8:9] op_sel:[0,1,0] op_sel_hi:[1,1,1]
	v_add_f32_dpp v15, v24, v24 row_ror:8 row_mask:0xf bank_mask:0xf bound_ctrl:1
	v_add_f32_dpp v32, v25, v25 row_ror:8 row_mask:0xf bank_mask:0xf bound_ctrl:1
	ds_read_b128 v[124:127], v48 offset:3072
	v_add_f32_dpp v15, v15, v15 row_ror:4 row_mask:0xf bank_mask:0xf bound_ctrl:1
	ds_read_b128 v[128:131], v48 offset:3328
	ds_read_b128 v[132:135], v48 offset:3584
	v_add_f32_dpp v15, v15, v15 row_ror:2 row_mask:0xf bank_mask:0xf bound_ctrl:1
	ds_read_b128 v[136:139], v48 offset:3840
	ds_read_b128 v[160:163], v49 offset:16
	v_add_f32_dpp v30, v15, v15 row_ror:1 row_mask:0xf bank_mask:0xf bound_ctrl:1
	s_waitcnt lgkmcnt(5)
	v_pk_fma_f32 v[10:11], v[96:97], v[30:31], v[16:17] op_sel_hi:[1,0,1] neg_lo:[0,1,0] neg_hi:[0,1,0]
	v_pk_fma_f32 v[8:9], v[98:99], v[30:31], v[18:19] op_sel_hi:[1,0,1] neg_lo:[0,1,0] neg_hi:[0,1,0]
	v_pk_mul_f32 v[24:25], v[10:11], v[100:101] op_sel:[0,0] op_sel_hi:[0,1]
	v_pk_fma_f32 v[24:25], v[10:11], v[102:103], v[24:25] op_sel:[1,0,0] op_sel_hi:[1,1,1]
	v_pk_fma_f32 v[24:25], v[8:9], v[104:105], v[24:25] op_sel:[0,0,0] op_sel_hi:[0,1,1]
	v_pk_fma_f32 v[24:25], v[8:9], v[106:107], v[24:25] op_sel:[1,0,0] op_sel_hi:[1,1,1]
	v_pk_fma_f32 v[16:17], v[108:109], v[158:159], v[10:11] op_sel_hi:[1,0,1]
	v_pk_fma_f32 v[18:19], v[110:111], v[158:159], v[8:9] op_sel_hi:[1,0,1]
	v_add_f32_dpp v15, v24, v24 row_ror:8 row_mask:0xf bank_mask:0xf bound_ctrl:1
	v_add_f32_dpp v33, v25, v25 row_ror:8 row_mask:0xf bank_mask:0xf bound_ctrl:1
	ds_read_b128 v[76:79], v48 offset:4096
	v_add_f32_dpp v15, v15, v15 row_ror:4 row_mask:0xf bank_mask:0xf bound_ctrl:1
	ds_read_b128 v[80:83], v48 offset:4352
	ds_read_b128 v[84:87], v48 offset:4608
	v_add_f32_dpp v15, v15, v15 row_ror:2 row_mask:0xf bank_mask:0xf bound_ctrl:1
	ds_read_b128 v[88:91], v48 offset:4864
	s_nop 0
	v_add_f32_dpp v30, v15, v15 row_ror:1 row_mask:0xf bank_mask:0xf bound_ctrl:1
	ds_write2st64_b32 v50, v32, v33 offset0:0 offset1:2
	s_waitcnt lgkmcnt(5)
	v_pk_fma_f32 v[10:11], v[112:113], v[30:31], v[16:17] op_sel_hi:[1,0,1] neg_lo:[0,1,0] neg_hi:[0,1,0]
	v_pk_fma_f32 v[8:9], v[114:115], v[30:31], v[18:19] op_sel_hi:[1,0,1] neg_lo:[0,1,0] neg_hi:[0,1,0]
	v_pk_mul_f32 v[24:25], v[10:11], v[116:117] op_sel:[0,0] op_sel_hi:[0,1]
	v_pk_fma_f32 v[24:25], v[10:11], v[118:119], v[24:25] op_sel:[1,0,0] op_sel_hi:[1,1,1]
	v_pk_fma_f32 v[24:25], v[8:9], v[120:121], v[24:25] op_sel:[0,0,0] op_sel_hi:[0,1,1]
	v_pk_fma_f32 v[24:25], v[8:9], v[122:123], v[24:25] op_sel:[1,0,0] op_sel_hi:[1,1,1]
	v_pk_fma_f32 v[16:17], v[124:125], v[158:159], v[10:11] op_sel:[0,1,0] op_sel_hi:[1,1,1]
	v_pk_fma_f32 v[18:19], v[126:127], v[158:159], v[8:9] op_sel:[0,1,0] op_sel_hi:[1,1,1]
	v_add_f32_dpp v15, v24, v24 row_ror:8 row_mask:0xf bank_mask:0xf bound_ctrl:1
	v_add_f32_dpp v32, v25, v25 row_ror:8 row_mask:0xf bank_mask:0xf bound_ctrl:1
	ds_read_b128 v[92:95], v48 offset:5120
	v_add_f32_dpp v15, v15, v15 row_ror:4 row_mask:0xf bank_mask:0xf bound_ctrl:1
	ds_read_b128 v[96:99], v48 offset:5376
	ds_read_b128 v[100:103], v48 offset:5632
	v_add_f32_dpp v15, v15, v15 row_ror:2 row_mask:0xf bank_mask:0xf bound_ctrl:1
	ds_read_b128 v[104:107], v48 offset:5888
	s_nop 0
	v_add_f32_dpp v30, v15, v15 row_ror:1 row_mask:0xf bank_mask:0xf bound_ctrl:1
	s_waitcnt lgkmcnt(4)
	v_pk_fma_f32 v[10:11], v[128:129], v[30:31], v[16:17] op_sel_hi:[1,0,1] neg_lo:[0,1,0] neg_hi:[0,1,0]
	v_pk_fma_f32 v[8:9], v[130:131], v[30:31], v[18:19] op_sel_hi:[1,0,1] neg_lo:[0,1,0] neg_hi:[0,1,0]
	v_pk_mul_f32 v[24:25], v[10:11], v[132:133] op_sel:[0,0] op_sel_hi:[0,1]
	v_pk_fma_f32 v[24:25], v[10:11], v[134:135], v[24:25] op_sel:[1,0,0] op_sel_hi:[1,1,1]
	v_pk_fma_f32 v[24:25], v[8:9], v[136:137], v[24:25] op_sel:[0,0,0] op_sel_hi:[0,1,1]
	v_pk_fma_f32 v[24:25], v[8:9], v[138:139], v[24:25] op_sel:[1,0,0] op_sel_hi:[1,1,1]
	v_pk_fma_f32 v[16:17], v[76:77], v[160:161], v[10:11] op_sel_hi:[1,0,1]
	v_pk_fma_f32 v[18:19], v[78:79], v[160:161], v[8:9] op_sel_hi:[1,0,1]
	v_add_f32_dpp v15, v24, v24 row_ror:8 row_mask:0xf bank_mask:0xf bound_ctrl:1
	v_add_f32_dpp v33, v25, v25 row_ror:8 row_mask:0xf bank_mask:0xf bound_ctrl:1
	ds_read_b128 v[108:111], v48 offset:6144
	v_add_f32_dpp v15, v15, v15 row_ror:4 row_mask:0xf bank_mask:0xf bound_ctrl:1
	ds_read_b128 v[112:115], v48 offset:6400
	ds_read_b128 v[116:119], v48 offset:6656
	v_add_f32_dpp v15, v15, v15 row_ror:2 row_mask:0xf bank_mask:0xf bound_ctrl:1
	ds_read_b128 v[120:123], v48 offset:6912
	ds_read_b128 v[140:143], v48 offset:33792
	v_add_f32_dpp v30, v15, v15 row_ror:1 row_mask:0xf bank_mask:0xf bound_ctrl:1
	ds_write2st64_b32 v50, v32, v33 offset0:4 offset1:6
	s_waitcnt lgkmcnt(6)
	v_pk_fma_f32 v[10:11], v[80:81], v[30:31], v[16:17] op_sel_hi:[1,0,1] neg_lo:[0,1,0] neg_hi:[0,1,0]
	v_pk_fma_f32 v[8:9], v[82:83], v[30:31], v[18:19] op_sel_hi:[1,0,1] neg_lo:[0,1,0] neg_hi:[0,1,0]
	v_pk_mul_f32 v[24:25], v[10:11], v[84:85] op_sel:[0,0] op_sel_hi:[0,1]
	v_pk_fma_f32 v[24:25], v[10:11], v[86:87], v[24:25] op_sel:[1,0,0] op_sel_hi:[1,1,1]
	v_pk_fma_f32 v[24:25], v[8:9], v[88:89], v[24:25] op_sel:[0,0,0] op_sel_hi:[0,1,1]
	v_pk_fma_f32 v[24:25], v[8:9], v[90:91], v[24:25] op_sel:[1,0,0] op_sel_hi:[1,1,1]
	v_pk_fma_f32 v[16:17], v[92:93], v[160:161], v[10:11] op_sel:[0,1,0] op_sel_hi:[1,1,1]
	v_pk_fma_f32 v[18:19], v[94:95], v[160:161], v[8:9] op_sel:[0,1,0] op_sel_hi:[1,1,1]
	v_add_f32_dpp v15, v24, v24 row_ror:8 row_mask:0xf bank_mask:0xf bound_ctrl:1
	v_add_f32_dpp v32, v25, v25 row_ror:8 row_mask:0xf bank_mask:0xf bound_ctrl:1
	ds_read_b128 v[124:127], v48 offset:7168
	v_add_f32_dpp v15, v15, v15 row_ror:4 row_mask:0xf bank_mask:0xf bound_ctrl:1
	ds_read_b128 v[128:131], v48 offset:7424
	ds_read_b128 v[132:135], v48 offset:7680
	v_add_f32_dpp v15, v15, v15 row_ror:2 row_mask:0xf bank_mask:0xf bound_ctrl:1
	ds_read_b128 v[136:139], v48 offset:7936
	ds_read_b128 v[156:159], v49 offset:32
	v_add_f32_dpp v30, v15, v15 row_ror:1 row_mask:0xf bank_mask:0xf bound_ctrl:1
	s_waitcnt lgkmcnt(5)
	v_pk_fma_f32 v[10:11], v[96:97], v[30:31], v[16:17] op_sel_hi:[1,0,1] neg_lo:[0,1,0] neg_hi:[0,1,0]
	v_pk_fma_f32 v[8:9], v[98:99], v[30:31], v[18:19] op_sel_hi:[1,0,1] neg_lo:[0,1,0] neg_hi:[0,1,0]
	v_pk_mul_f32 v[24:25], v[10:11], v[100:101] op_sel:[0,0] op_sel_hi:[0,1]
	v_pk_fma_f32 v[24:25], v[10:11], v[102:103], v[24:25] op_sel:[1,0,0] op_sel_hi:[1,1,1]
	v_pk_fma_f32 v[24:25], v[8:9], v[104:105], v[24:25] op_sel:[0,0,0] op_sel_hi:[0,1,1]
	v_pk_fma_f32 v[24:25], v[8:9], v[106:107], v[24:25] op_sel:[1,0,0] op_sel_hi:[1,1,1]
	v_pk_fma_f32 v[16:17], v[108:109], v[162:163], v[10:11] op_sel_hi:[1,0,1]
	v_pk_fma_f32 v[18:19], v[110:111], v[162:163], v[8:9] op_sel_hi:[1,0,1]
	v_add_f32_dpp v15, v24, v24 row_ror:8 row_mask:0xf bank_mask:0xf bound_ctrl:1
	v_add_f32_dpp v33, v25, v25 row_ror:8 row_mask:0xf bank_mask:0xf bound_ctrl:1
	ds_read_b128 v[76:79], v48 offset:8192
	v_add_f32_dpp v15, v15, v15 row_ror:4 row_mask:0xf bank_mask:0xf bound_ctrl:1
	ds_read_b128 v[80:83], v48 offset:8448
	ds_read_b128 v[84:87], v48 offset:8704
	v_add_f32_dpp v15, v15, v15 row_ror:2 row_mask:0xf bank_mask:0xf bound_ctrl:1
	ds_read_b128 v[88:91], v48 offset:8960
	ds_read_b128 v[144:147], v48 offset:33024
	v_add_f32_dpp v30, v15, v15 row_ror:1 row_mask:0xf bank_mask:0xf bound_ctrl:1
	ds_write2st64_b32 v50, v32, v33 offset0:8 offset1:10
	s_waitcnt lgkmcnt(6)
	v_pk_fma_f32 v[10:11], v[112:113], v[30:31], v[16:17] op_sel_hi:[1,0,1] neg_lo:[0,1,0] neg_hi:[0,1,0]
	v_pk_fma_f32 v[8:9], v[114:115], v[30:31], v[18:19] op_sel_hi:[1,0,1] neg_lo:[0,1,0] neg_hi:[0,1,0]
	v_pk_mul_f32 v[24:25], v[10:11], v[116:117] op_sel:[0,0] op_sel_hi:[0,1]
	v_pk_fma_f32 v[24:25], v[10:11], v[118:119], v[24:25] op_sel:[1,0,0] op_sel_hi:[1,1,1]
	v_pk_fma_f32 v[24:25], v[8:9], v[120:121], v[24:25] op_sel:[0,0,0] op_sel_hi:[0,1,1]
	v_pk_fma_f32 v[24:25], v[8:9], v[122:123], v[24:25] op_sel:[1,0,0] op_sel_hi:[1,1,1]
	v_pk_fma_f32 v[16:17], v[124:125], v[162:163], v[10:11] op_sel:[0,1,0] op_sel_hi:[1,1,1]
	v_pk_fma_f32 v[18:19], v[126:127], v[162:163], v[8:9] op_sel:[0,1,0] op_sel_hi:[1,1,1]
	v_add_f32_dpp v15, v24, v24 row_ror:8 row_mask:0xf bank_mask:0xf bound_ctrl:1
	v_add_f32_dpp v32, v25, v25 row_ror:8 row_mask:0xf bank_mask:0xf bound_ctrl:1
	ds_read_b128 v[92:95], v48 offset:9216
	v_add_f32_dpp v15, v15, v15 row_ror:4 row_mask:0xf bank_mask:0xf bound_ctrl:1
	ds_read_b128 v[96:99], v48 offset:9472
	ds_read_b128 v[100:103], v48 offset:9728
	v_add_f32_dpp v15, v15, v15 row_ror:2 row_mask:0xf bank_mask:0xf bound_ctrl:1
	ds_read_b128 v[104:107], v48 offset:9984
	s_nop 0
	v_add_f32_dpp v30, v15, v15 row_ror:1 row_mask:0xf bank_mask:0xf bound_ctrl:1
	s_waitcnt lgkmcnt(4)
	v_pk_fma_f32 v[10:11], v[128:129], v[30:31], v[16:17] op_sel_hi:[1,0,1] neg_lo:[0,1,0] neg_hi:[0,1,0]
	v_pk_fma_f32 v[8:9], v[130:131], v[30:31], v[18:19] op_sel_hi:[1,0,1] neg_lo:[0,1,0] neg_hi:[0,1,0]
	v_pk_mul_f32 v[24:25], v[10:11], v[132:133] op_sel:[0,0] op_sel_hi:[0,1]
	v_pk_fma_f32 v[24:25], v[10:11], v[134:135], v[24:25] op_sel:[1,0,0] op_sel_hi:[1,1,1]
	v_pk_fma_f32 v[24:25], v[8:9], v[136:137], v[24:25] op_sel:[0,0,0] op_sel_hi:[0,1,1]
	v_pk_fma_f32 v[24:25], v[8:9], v[138:139], v[24:25] op_sel:[1,0,0] op_sel_hi:[1,1,1]
	s_nop 1
	v_add_f32_dpp v33, v25, v25 row_ror:8 row_mask:0xf bank_mask:0xf bound_ctrl:1
	ds_write2st64_b32 v50, v32, v33 offset0:12 offset1:14
	v_pk_mul_f32 v[10:11], v[10:11], v[140:141]
	v_pk_mul_f32 v[8:9], v[8:9], v[142:143]
	v_pk_mul_f32 v[24:25], v[10:11], v[144:145]
	v_pk_fma_f32 v[24:25], v[8:9], v[146:147], v[24:25]
	v_add_f32_e32 v24, v24, v25
	v_pk_fma_f32 v[16:17], v[76:77], v[156:157], v[10:11] op_sel_hi:[1,0,1]
	v_pk_fma_f32 v[18:19], v[78:79], v[156:157], v[8:9] op_sel_hi:[1,0,1]
	v_add_f32_dpp v15, v24, v24 row_ror:8 row_mask:0xf bank_mask:0xf bound_ctrl:1
	ds_read_b128 v[108:111], v48 offset:10240
	ds_read_b128 v[112:115], v48 offset:10496
	v_add_f32_dpp v15, v15, v15 row_ror:4 row_mask:0xf bank_mask:0xf bound_ctrl:1
	ds_read_b128 v[116:119], v48 offset:10752
	ds_read_b128 v[120:123], v48 offset:11008
	v_add_f32_dpp v15, v15, v15 row_ror:2 row_mask:0xf bank_mask:0xf bound_ctrl:1
	s_nop 1
	v_add_f32_dpp v30, v15, v15 row_ror:1 row_mask:0xf bank_mask:0xf bound_ctrl:1
	s_waitcnt lgkmcnt(5)
	v_pk_fma_f32 v[10:11], v[80:81], v[30:31], v[16:17] op_sel_hi:[1,0,1] neg_lo:[0,1,0] neg_hi:[0,1,0]
	v_pk_fma_f32 v[8:9], v[82:83], v[30:31], v[18:19] op_sel_hi:[1,0,1] neg_lo:[0,1,0] neg_hi:[0,1,0]
	v_pk_mul_f32 v[24:25], v[10:11], v[84:85] op_sel:[0,0] op_sel_hi:[0,1]
	v_pk_fma_f32 v[24:25], v[10:11], v[86:87], v[24:25] op_sel:[1,0,0] op_sel_hi:[1,1,1]
	v_pk_fma_f32 v[24:25], v[8:9], v[88:89], v[24:25] op_sel:[0,0,0] op_sel_hi:[0,1,1]
	v_pk_fma_f32 v[24:25], v[8:9], v[90:91], v[24:25] op_sel:[1,0,0] op_sel_hi:[1,1,1]
	v_pk_fma_f32 v[16:17], v[92:93], v[156:157], v[10:11] op_sel:[0,1,0] op_sel_hi:[1,1,1]
	v_pk_fma_f32 v[18:19], v[94:95], v[156:157], v[8:9] op_sel:[0,1,0] op_sel_hi:[1,1,1]
	v_add_f32_dpp v15, v24, v24 row_ror:8 row_mask:0xf bank_mask:0xf bound_ctrl:1
	v_add_f32_dpp v32, v25, v25 row_ror:8 row_mask:0xf bank_mask:0xf bound_ctrl:1
	ds_read_b128 v[124:127], v48 offset:11264
	v_add_f32_dpp v15, v15, v15 row_ror:4 row_mask:0xf bank_mask:0xf bound_ctrl:1
	ds_read_b128 v[128:131], v48 offset:11520
	ds_read_b128 v[132:135], v48 offset:11776
	v_add_f32_dpp v15, v15, v15 row_ror:2 row_mask:0xf bank_mask:0xf bound_ctrl:1
	ds_read_b128 v[136:139], v48 offset:12032
	ds_read_b128 v[160:163], v49 offset:48
	v_add_f32_dpp v30, v15, v15 row_ror:1 row_mask:0xf bank_mask:0xf bound_ctrl:1
	s_waitcnt lgkmcnt(5)
	v_pk_fma_f32 v[10:11], v[96:97], v[30:31], v[16:17] op_sel_hi:[1,0,1] neg_lo:[0,1,0] neg_hi:[0,1,0]
	v_pk_fma_f32 v[8:9], v[98:99], v[30:31], v[18:19] op_sel_hi:[1,0,1] neg_lo:[0,1,0] neg_hi:[0,1,0]
	v_pk_mul_f32 v[24:25], v[10:11], v[100:101] op_sel:[0,0] op_sel_hi:[0,1]
	v_pk_fma_f32 v[24:25], v[10:11], v[102:103], v[24:25] op_sel:[1,0,0] op_sel_hi:[1,1,1]
	v_pk_fma_f32 v[24:25], v[8:9], v[104:105], v[24:25] op_sel:[0,0,0] op_sel_hi:[0,1,1]
	v_pk_fma_f32 v[24:25], v[8:9], v[106:107], v[24:25] op_sel:[1,0,0] op_sel_hi:[1,1,1]
	v_pk_fma_f32 v[16:17], v[108:109], v[158:159], v[10:11] op_sel_hi:[1,0,1]
	v_pk_fma_f32 v[18:19], v[110:111], v[158:159], v[8:9] op_sel_hi:[1,0,1]
	v_add_f32_dpp v15, v24, v24 row_ror:8 row_mask:0xf bank_mask:0xf bound_ctrl:1
	v_add_f32_dpp v33, v25, v25 row_ror:8 row_mask:0xf bank_mask:0xf bound_ctrl:1
	ds_read_b128 v[76:79], v48 offset:12288
	v_add_f32_dpp v15, v15, v15 row_ror:4 row_mask:0xf bank_mask:0xf bound_ctrl:1
	ds_read_b128 v[80:83], v48 offset:12544
	ds_read_b128 v[84:87], v48 offset:12800
	v_add_f32_dpp v15, v15, v15 row_ror:2 row_mask:0xf bank_mask:0xf bound_ctrl:1
	ds_read_b128 v[88:91], v48 offset:13056
	s_nop 0
	v_add_f32_dpp v30, v15, v15 row_ror:1 row_mask:0xf bank_mask:0xf bound_ctrl:1
	ds_write2st64_b32 v50, v32, v33 offset0:16 offset1:18
	s_waitcnt lgkmcnt(5)
	v_pk_fma_f32 v[10:11], v[112:113], v[30:31], v[16:17] op_sel_hi:[1,0,1] neg_lo:[0,1,0] neg_hi:[0,1,0]
	v_pk_fma_f32 v[8:9], v[114:115], v[30:31], v[18:19] op_sel_hi:[1,0,1] neg_lo:[0,1,0] neg_hi:[0,1,0]
	v_pk_mul_f32 v[24:25], v[10:11], v[116:117] op_sel:[0,0] op_sel_hi:[0,1]
	v_pk_fma_f32 v[24:25], v[10:11], v[118:119], v[24:25] op_sel:[1,0,0] op_sel_hi:[1,1,1]
	v_pk_fma_f32 v[24:25], v[8:9], v[120:121], v[24:25] op_sel:[0,0,0] op_sel_hi:[0,1,1]
	v_pk_fma_f32 v[24:25], v[8:9], v[122:123], v[24:25] op_sel:[1,0,0] op_sel_hi:[1,1,1]
	v_pk_fma_f32 v[16:17], v[124:125], v[158:159], v[10:11] op_sel:[0,1,0] op_sel_hi:[1,1,1]
	v_pk_fma_f32 v[18:19], v[126:127], v[158:159], v[8:9] op_sel:[0,1,0] op_sel_hi:[1,1,1]
	v_add_f32_dpp v15, v24, v24 row_ror:8 row_mask:0xf bank_mask:0xf bound_ctrl:1
	v_add_f32_dpp v32, v25, v25 row_ror:8 row_mask:0xf bank_mask:0xf bound_ctrl:1
	ds_read_b128 v[92:95], v48 offset:13312
	v_add_f32_dpp v15, v15, v15 row_ror:4 row_mask:0xf bank_mask:0xf bound_ctrl:1
	ds_read_b128 v[96:99], v48 offset:13568
	ds_read_b128 v[100:103], v48 offset:13824
	v_add_f32_dpp v15, v15, v15 row_ror:2 row_mask:0xf bank_mask:0xf bound_ctrl:1
	ds_read_b128 v[104:107], v48 offset:14080
	s_nop 0
	v_add_f32_dpp v30, v15, v15 row_ror:1 row_mask:0xf bank_mask:0xf bound_ctrl:1
	s_waitcnt lgkmcnt(4)
	v_pk_fma_f32 v[10:11], v[128:129], v[30:31], v[16:17] op_sel_hi:[1,0,1] neg_lo:[0,1,0] neg_hi:[0,1,0]
	v_pk_fma_f32 v[8:9], v[130:131], v[30:31], v[18:19] op_sel_hi:[1,0,1] neg_lo:[0,1,0] neg_hi:[0,1,0]
	v_pk_mul_f32 v[24:25], v[10:11], v[132:133] op_sel:[0,0] op_sel_hi:[0,1]
	v_pk_fma_f32 v[24:25], v[10:11], v[134:135], v[24:25] op_sel:[1,0,0] op_sel_hi:[1,1,1]
	v_pk_fma_f32 v[24:25], v[8:9], v[136:137], v[24:25] op_sel:[0,0,0] op_sel_hi:[0,1,1]
	v_pk_fma_f32 v[24:25], v[8:9], v[138:139], v[24:25] op_sel:[1,0,0] op_sel_hi:[1,1,1]
	v_pk_fma_f32 v[16:17], v[76:77], v[160:161], v[10:11] op_sel_hi:[1,0,1]
	v_pk_fma_f32 v[18:19], v[78:79], v[160:161], v[8:9] op_sel_hi:[1,0,1]
	v_add_f32_dpp v15, v24, v24 row_ror:8 row_mask:0xf bank_mask:0xf bound_ctrl:1
	v_add_f32_dpp v33, v25, v25 row_ror:8 row_mask:0xf bank_mask:0xf bound_ctrl:1
	ds_read_b128 v[108:111], v48 offset:14336
	v_add_f32_dpp v15, v15, v15 row_ror:4 row_mask:0xf bank_mask:0xf bound_ctrl:1
	ds_read_b128 v[112:115], v48 offset:14592
	ds_read_b128 v[116:119], v48 offset:14848
	v_add_f32_dpp v15, v15, v15 row_ror:2 row_mask:0xf bank_mask:0xf bound_ctrl:1
	ds_read_b128 v[120:123], v48 offset:15104
	ds_read_b128 v[140:143], v48 offset:34048
	v_add_f32_dpp v30, v15, v15 row_ror:1 row_mask:0xf bank_mask:0xf bound_ctrl:1
	ds_write2st64_b32 v50, v32, v33 offset0:20 offset1:22
	s_waitcnt lgkmcnt(6)
	v_pk_fma_f32 v[10:11], v[80:81], v[30:31], v[16:17] op_sel_hi:[1,0,1] neg_lo:[0,1,0] neg_hi:[0,1,0]
	v_pk_fma_f32 v[8:9], v[82:83], v[30:31], v[18:19] op_sel_hi:[1,0,1] neg_lo:[0,1,0] neg_hi:[0,1,0]
	v_pk_mul_f32 v[24:25], v[10:11], v[84:85] op_sel:[0,0] op_sel_hi:[0,1]
	v_pk_fma_f32 v[24:25], v[10:11], v[86:87], v[24:25] op_sel:[1,0,0] op_sel_hi:[1,1,1]
	v_pk_fma_f32 v[24:25], v[8:9], v[88:89], v[24:25] op_sel:[0,0,0] op_sel_hi:[0,1,1]
	v_pk_fma_f32 v[24:25], v[8:9], v[90:91], v[24:25] op_sel:[1,0,0] op_sel_hi:[1,1,1]
	v_pk_fma_f32 v[16:17], v[92:93], v[160:161], v[10:11] op_sel:[0,1,0] op_sel_hi:[1,1,1]
	v_pk_fma_f32 v[18:19], v[94:95], v[160:161], v[8:9] op_sel:[0,1,0] op_sel_hi:[1,1,1]
	v_add_f32_dpp v15, v24, v24 row_ror:8 row_mask:0xf bank_mask:0xf bound_ctrl:1
	v_add_f32_dpp v32, v25, v25 row_ror:8 row_mask:0xf bank_mask:0xf bound_ctrl:1
	ds_read_b128 v[124:127], v48 offset:15360
	v_add_f32_dpp v15, v15, v15 row_ror:4 row_mask:0xf bank_mask:0xf bound_ctrl:1
	ds_read_b128 v[128:131], v48 offset:15616
	ds_read_b128 v[132:135], v48 offset:15872
	v_add_f32_dpp v15, v15, v15 row_ror:2 row_mask:0xf bank_mask:0xf bound_ctrl:1
	ds_read_b128 v[136:139], v48 offset:16128
	ds_read_b128 v[156:159], v49 offset:64
	v_add_f32_dpp v30, v15, v15 row_ror:1 row_mask:0xf bank_mask:0xf bound_ctrl:1
	s_waitcnt lgkmcnt(5)
	v_pk_fma_f32 v[10:11], v[96:97], v[30:31], v[16:17] op_sel_hi:[1,0,1] neg_lo:[0,1,0] neg_hi:[0,1,0]
	v_pk_fma_f32 v[8:9], v[98:99], v[30:31], v[18:19] op_sel_hi:[1,0,1] neg_lo:[0,1,0] neg_hi:[0,1,0]
	v_pk_mul_f32 v[24:25], v[10:11], v[100:101] op_sel:[0,0] op_sel_hi:[0,1]
	v_pk_fma_f32 v[24:25], v[10:11], v[102:103], v[24:25] op_sel:[1,0,0] op_sel_hi:[1,1,1]
	v_pk_fma_f32 v[24:25], v[8:9], v[104:105], v[24:25] op_sel:[0,0,0] op_sel_hi:[0,1,1]
	v_pk_fma_f32 v[24:25], v[8:9], v[106:107], v[24:25] op_sel:[1,0,0] op_sel_hi:[1,1,1]
	v_pk_fma_f32 v[16:17], v[108:109], v[162:163], v[10:11] op_sel_hi:[1,0,1]
	v_pk_fma_f32 v[18:19], v[110:111], v[162:163], v[8:9] op_sel_hi:[1,0,1]
	v_add_f32_dpp v15, v24, v24 row_ror:8 row_mask:0xf bank_mask:0xf bound_ctrl:1
	v_add_f32_dpp v33, v25, v25 row_ror:8 row_mask:0xf bank_mask:0xf bound_ctrl:1
	ds_read_b128 v[76:79], v48 offset:16384
	v_add_f32_dpp v15, v15, v15 row_ror:4 row_mask:0xf bank_mask:0xf bound_ctrl:1
	ds_read_b128 v[80:83], v48 offset:16640
	ds_read_b128 v[84:87], v48 offset:16896
	v_add_f32_dpp v15, v15, v15 row_ror:2 row_mask:0xf bank_mask:0xf bound_ctrl:1
	ds_read_b128 v[88:91], v48 offset:17152
	ds_read_b128 v[144:147], v48 offset:33280
	v_add_f32_dpp v30, v15, v15 row_ror:1 row_mask:0xf bank_mask:0xf bound_ctrl:1
	ds_write2st64_b32 v50, v32, v33 offset0:24 offset1:26
	s_waitcnt lgkmcnt(6)
	v_pk_fma_f32 v[10:11], v[112:113], v[30:31], v[16:17] op_sel_hi:[1,0,1] neg_lo:[0,1,0] neg_hi:[0,1,0]
	v_pk_fma_f32 v[8:9], v[114:115], v[30:31], v[18:19] op_sel_hi:[1,0,1] neg_lo:[0,1,0] neg_hi:[0,1,0]
	v_pk_mul_f32 v[24:25], v[10:11], v[116:117] op_sel:[0,0] op_sel_hi:[0,1]
	v_pk_fma_f32 v[24:25], v[10:11], v[118:119], v[24:25] op_sel:[1,0,0] op_sel_hi:[1,1,1]
	v_pk_fma_f32 v[24:25], v[8:9], v[120:121], v[24:25] op_sel:[0,0,0] op_sel_hi:[0,1,1]
	v_pk_fma_f32 v[24:25], v[8:9], v[122:123], v[24:25] op_sel:[1,0,0] op_sel_hi:[1,1,1]
	v_pk_fma_f32 v[16:17], v[124:125], v[162:163], v[10:11] op_sel:[0,1,0] op_sel_hi:[1,1,1]
	v_pk_fma_f32 v[18:19], v[126:127], v[162:163], v[8:9] op_sel:[0,1,0] op_sel_hi:[1,1,1]
	v_add_f32_dpp v15, v24, v24 row_ror:8 row_mask:0xf bank_mask:0xf bound_ctrl:1
	v_add_f32_dpp v32, v25, v25 row_ror:8 row_mask:0xf bank_mask:0xf bound_ctrl:1
	ds_read_b128 v[92:95], v48 offset:17408
	v_add_f32_dpp v15, v15, v15 row_ror:4 row_mask:0xf bank_mask:0xf bound_ctrl:1
	ds_read_b128 v[96:99], v48 offset:17664
	ds_read_b128 v[100:103], v48 offset:17920
	v_add_f32_dpp v15, v15, v15 row_ror:2 row_mask:0xf bank_mask:0xf bound_ctrl:1
	ds_read_b128 v[104:107], v48 offset:18176
	s_nop 0
	v_add_f32_dpp v30, v15, v15 row_ror:1 row_mask:0xf bank_mask:0xf bound_ctrl:1
	s_waitcnt lgkmcnt(4)
	v_pk_fma_f32 v[10:11], v[128:129], v[30:31], v[16:17] op_sel_hi:[1,0,1] neg_lo:[0,1,0] neg_hi:[0,1,0]
	v_pk_fma_f32 v[8:9], v[130:131], v[30:31], v[18:19] op_sel_hi:[1,0,1] neg_lo:[0,1,0] neg_hi:[0,1,0]
	v_pk_mul_f32 v[24:25], v[10:11], v[132:133] op_sel:[0,0] op_sel_hi:[0,1]
	v_pk_fma_f32 v[24:25], v[10:11], v[134:135], v[24:25] op_sel:[1,0,0] op_sel_hi:[1,1,1]
	v_pk_fma_f32 v[24:25], v[8:9], v[136:137], v[24:25] op_sel:[0,0,0] op_sel_hi:[0,1,1]
	v_pk_fma_f32 v[24:25], v[8:9], v[138:139], v[24:25] op_sel:[1,0,0] op_sel_hi:[1,1,1]
	s_nop 1
	v_add_f32_dpp v33, v25, v25 row_ror:8 row_mask:0xf bank_mask:0xf bound_ctrl:1
	ds_write2st64_b32 v50, v32, v33 offset0:28 offset1:30
	v_pk_mul_f32 v[10:11], v[10:11], v[140:141]
	v_pk_mul_f32 v[8:9], v[8:9], v[142:143]
	v_pk_mul_f32 v[24:25], v[10:11], v[144:145]
	v_pk_fma_f32 v[24:25], v[8:9], v[146:147], v[24:25]
	v_add_f32_e32 v24, v24, v25
	v_pk_fma_f32 v[16:17], v[76:77], v[156:157], v[10:11] op_sel_hi:[1,0,1]
	v_pk_fma_f32 v[18:19], v[78:79], v[156:157], v[8:9] op_sel_hi:[1,0,1]
	v_add_f32_dpp v15, v24, v24 row_ror:8 row_mask:0xf bank_mask:0xf bound_ctrl:1
	ds_read_b128 v[108:111], v48 offset:18432
	ds_read_b128 v[112:115], v48 offset:18688
	v_add_f32_dpp v15, v15, v15 row_ror:4 row_mask:0xf bank_mask:0xf bound_ctrl:1
	ds_read_b128 v[116:119], v48 offset:18944
	ds_read_b128 v[120:123], v48 offset:19200
	v_add_f32_dpp v15, v15, v15 row_ror:2 row_mask:0xf bank_mask:0xf bound_ctrl:1
	s_nop 1
	v_add_f32_dpp v30, v15, v15 row_ror:1 row_mask:0xf bank_mask:0xf bound_ctrl:1
	s_waitcnt lgkmcnt(5)
	v_pk_fma_f32 v[10:11], v[80:81], v[30:31], v[16:17] op_sel_hi:[1,0,1] neg_lo:[0,1,0] neg_hi:[0,1,0]
	v_pk_fma_f32 v[8:9], v[82:83], v[30:31], v[18:19] op_sel_hi:[1,0,1] neg_lo:[0,1,0] neg_hi:[0,1,0]
	v_pk_mul_f32 v[24:25], v[10:11], v[84:85] op_sel:[0,0] op_sel_hi:[0,1]
	v_pk_fma_f32 v[24:25], v[10:11], v[86:87], v[24:25] op_sel:[1,0,0] op_sel_hi:[1,1,1]
	v_pk_fma_f32 v[24:25], v[8:9], v[88:89], v[24:25] op_sel:[0,0,0] op_sel_hi:[0,1,1]
	v_pk_fma_f32 v[24:25], v[8:9], v[90:91], v[24:25] op_sel:[1,0,0] op_sel_hi:[1,1,1]
	v_pk_fma_f32 v[16:17], v[92:93], v[156:157], v[10:11] op_sel:[0,1,0] op_sel_hi:[1,1,1]
	v_pk_fma_f32 v[18:19], v[94:95], v[156:157], v[8:9] op_sel:[0,1,0] op_sel_hi:[1,1,1]
	v_add_f32_dpp v15, v24, v24 row_ror:8 row_mask:0xf bank_mask:0xf bound_ctrl:1
	v_add_f32_dpp v32, v25, v25 row_ror:8 row_mask:0xf bank_mask:0xf bound_ctrl:1
	ds_read_b128 v[124:127], v48 offset:19456
	v_add_f32_dpp v15, v15, v15 row_ror:4 row_mask:0xf bank_mask:0xf bound_ctrl:1
	ds_read_b128 v[128:131], v48 offset:19712
	ds_read_b128 v[132:135], v48 offset:19968
	v_add_f32_dpp v15, v15, v15 row_ror:2 row_mask:0xf bank_mask:0xf bound_ctrl:1
	ds_read_b128 v[136:139], v48 offset:20224
	ds_read_b128 v[160:163], v49 offset:80
	v_add_f32_dpp v30, v15, v15 row_ror:1 row_mask:0xf bank_mask:0xf bound_ctrl:1
	s_waitcnt lgkmcnt(5)
	v_pk_fma_f32 v[10:11], v[96:97], v[30:31], v[16:17] op_sel_hi:[1,0,1] neg_lo:[0,1,0] neg_hi:[0,1,0]
	v_pk_fma_f32 v[8:9], v[98:99], v[30:31], v[18:19] op_sel_hi:[1,0,1] neg_lo:[0,1,0] neg_hi:[0,1,0]
	v_pk_mul_f32 v[24:25], v[10:11], v[100:101] op_sel:[0,0] op_sel_hi:[0,1]
	v_pk_fma_f32 v[24:25], v[10:11], v[102:103], v[24:25] op_sel:[1,0,0] op_sel_hi:[1,1,1]
	v_pk_fma_f32 v[24:25], v[8:9], v[104:105], v[24:25] op_sel:[0,0,0] op_sel_hi:[0,1,1]
	v_pk_fma_f32 v[24:25], v[8:9], v[106:107], v[24:25] op_sel:[1,0,0] op_sel_hi:[1,1,1]
	v_pk_fma_f32 v[16:17], v[108:109], v[158:159], v[10:11] op_sel_hi:[1,0,1]
	v_pk_fma_f32 v[18:19], v[110:111], v[158:159], v[8:9] op_sel_hi:[1,0,1]
	v_add_f32_dpp v15, v24, v24 row_ror:8 row_mask:0xf bank_mask:0xf bound_ctrl:1
	v_add_f32_dpp v33, v25, v25 row_ror:8 row_mask:0xf bank_mask:0xf bound_ctrl:1
	ds_read_b128 v[76:79], v48 offset:20480
	v_add_f32_dpp v15, v15, v15 row_ror:4 row_mask:0xf bank_mask:0xf bound_ctrl:1
	ds_read_b128 v[80:83], v48 offset:20736
	ds_read_b128 v[84:87], v48 offset:20992
	v_add_f32_dpp v15, v15, v15 row_ror:2 row_mask:0xf bank_mask:0xf bound_ctrl:1
	ds_read_b128 v[88:91], v48 offset:21248
	s_nop 0
	v_add_f32_dpp v30, v15, v15 row_ror:1 row_mask:0xf bank_mask:0xf bound_ctrl:1
	ds_write2st64_b32 v50, v32, v33 offset0:32 offset1:34
	s_waitcnt lgkmcnt(5)
	v_pk_fma_f32 v[10:11], v[112:113], v[30:31], v[16:17] op_sel_hi:[1,0,1] neg_lo:[0,1,0] neg_hi:[0,1,0]
	v_pk_fma_f32 v[8:9], v[114:115], v[30:31], v[18:19] op_sel_hi:[1,0,1] neg_lo:[0,1,0] neg_hi:[0,1,0]
	v_pk_mul_f32 v[24:25], v[10:11], v[116:117] op_sel:[0,0] op_sel_hi:[0,1]
	v_pk_fma_f32 v[24:25], v[10:11], v[118:119], v[24:25] op_sel:[1,0,0] op_sel_hi:[1,1,1]
	v_pk_fma_f32 v[24:25], v[8:9], v[120:121], v[24:25] op_sel:[0,0,0] op_sel_hi:[0,1,1]
	v_pk_fma_f32 v[24:25], v[8:9], v[122:123], v[24:25] op_sel:[1,0,0] op_sel_hi:[1,1,1]
	v_pk_fma_f32 v[16:17], v[124:125], v[158:159], v[10:11] op_sel:[0,1,0] op_sel_hi:[1,1,1]
	v_pk_fma_f32 v[18:19], v[126:127], v[158:159], v[8:9] op_sel:[0,1,0] op_sel_hi:[1,1,1]
	v_add_f32_dpp v15, v24, v24 row_ror:8 row_mask:0xf bank_mask:0xf bound_ctrl:1
	v_add_f32_dpp v32, v25, v25 row_ror:8 row_mask:0xf bank_mask:0xf bound_ctrl:1
	ds_read_b128 v[92:95], v48 offset:21504
	v_add_f32_dpp v15, v15, v15 row_ror:4 row_mask:0xf bank_mask:0xf bound_ctrl:1
	ds_read_b128 v[96:99], v48 offset:21760
	ds_read_b128 v[100:103], v48 offset:22016
	v_add_f32_dpp v15, v15, v15 row_ror:2 row_mask:0xf bank_mask:0xf bound_ctrl:1
	ds_read_b128 v[104:107], v48 offset:22272
	s_nop 0
	v_add_f32_dpp v30, v15, v15 row_ror:1 row_mask:0xf bank_mask:0xf bound_ctrl:1
	s_waitcnt lgkmcnt(4)
	v_pk_fma_f32 v[10:11], v[128:129], v[30:31], v[16:17] op_sel_hi:[1,0,1] neg_lo:[0,1,0] neg_hi:[0,1,0]
	v_pk_fma_f32 v[8:9], v[130:131], v[30:31], v[18:19] op_sel_hi:[1,0,1] neg_lo:[0,1,0] neg_hi:[0,1,0]
	v_pk_mul_f32 v[24:25], v[10:11], v[132:133] op_sel:[0,0] op_sel_hi:[0,1]
	v_pk_fma_f32 v[24:25], v[10:11], v[134:135], v[24:25] op_sel:[1,0,0] op_sel_hi:[1,1,1]
	v_pk_fma_f32 v[24:25], v[8:9], v[136:137], v[24:25] op_sel:[0,0,0] op_sel_hi:[0,1,1]
	v_pk_fma_f32 v[24:25], v[8:9], v[138:139], v[24:25] op_sel:[1,0,0] op_sel_hi:[1,1,1]
	v_pk_fma_f32 v[16:17], v[76:77], v[160:161], v[10:11] op_sel_hi:[1,0,1]
	v_pk_fma_f32 v[18:19], v[78:79], v[160:161], v[8:9] op_sel_hi:[1,0,1]
	v_add_f32_dpp v15, v24, v24 row_ror:8 row_mask:0xf bank_mask:0xf bound_ctrl:1
	v_add_f32_dpp v33, v25, v25 row_ror:8 row_mask:0xf bank_mask:0xf bound_ctrl:1
	ds_read_b128 v[108:111], v48 offset:22528
	v_add_f32_dpp v15, v15, v15 row_ror:4 row_mask:0xf bank_mask:0xf bound_ctrl:1
	ds_read_b128 v[112:115], v48 offset:22784
	ds_read_b128 v[116:119], v48 offset:23040
	v_add_f32_dpp v15, v15, v15 row_ror:2 row_mask:0xf bank_mask:0xf bound_ctrl:1
	ds_read_b128 v[120:123], v48 offset:23296
	ds_read_b128 v[140:143], v48 offset:34304
	v_add_f32_dpp v30, v15, v15 row_ror:1 row_mask:0xf bank_mask:0xf bound_ctrl:1
	ds_write2st64_b32 v50, v32, v33 offset0:36 offset1:38
	s_waitcnt lgkmcnt(6)
	v_pk_fma_f32 v[10:11], v[80:81], v[30:31], v[16:17] op_sel_hi:[1,0,1] neg_lo:[0,1,0] neg_hi:[0,1,0]
	v_pk_fma_f32 v[8:9], v[82:83], v[30:31], v[18:19] op_sel_hi:[1,0,1] neg_lo:[0,1,0] neg_hi:[0,1,0]
	v_pk_mul_f32 v[24:25], v[10:11], v[84:85] op_sel:[0,0] op_sel_hi:[0,1]
	v_pk_fma_f32 v[24:25], v[10:11], v[86:87], v[24:25] op_sel:[1,0,0] op_sel_hi:[1,1,1]
	v_pk_fma_f32 v[24:25], v[8:9], v[88:89], v[24:25] op_sel:[0,0,0] op_sel_hi:[0,1,1]
	v_pk_fma_f32 v[24:25], v[8:9], v[90:91], v[24:25] op_sel:[1,0,0] op_sel_hi:[1,1,1]
	v_pk_fma_f32 v[16:17], v[92:93], v[160:161], v[10:11] op_sel:[0,1,0] op_sel_hi:[1,1,1]
	v_pk_fma_f32 v[18:19], v[94:95], v[160:161], v[8:9] op_sel:[0,1,0] op_sel_hi:[1,1,1]
	v_add_f32_dpp v15, v24, v24 row_ror:8 row_mask:0xf bank_mask:0xf bound_ctrl:1
	v_add_f32_dpp v32, v25, v25 row_ror:8 row_mask:0xf bank_mask:0xf bound_ctrl:1
	ds_read_b128 v[124:127], v48 offset:23552
	v_add_f32_dpp v15, v15, v15 row_ror:4 row_mask:0xf bank_mask:0xf bound_ctrl:1
	ds_read_b128 v[128:131], v48 offset:23808
	ds_read_b128 v[132:135], v48 offset:24064
	v_add_f32_dpp v15, v15, v15 row_ror:2 row_mask:0xf bank_mask:0xf bound_ctrl:1
	ds_read_b128 v[136:139], v48 offset:24320
	ds_read_b128 v[156:159], v49 offset:96
	v_add_f32_dpp v30, v15, v15 row_ror:1 row_mask:0xf bank_mask:0xf bound_ctrl:1
	s_waitcnt lgkmcnt(5)
	v_pk_fma_f32 v[10:11], v[96:97], v[30:31], v[16:17] op_sel_hi:[1,0,1] neg_lo:[0,1,0] neg_hi:[0,1,0]
	v_pk_fma_f32 v[8:9], v[98:99], v[30:31], v[18:19] op_sel_hi:[1,0,1] neg_lo:[0,1,0] neg_hi:[0,1,0]
	v_pk_mul_f32 v[24:25], v[10:11], v[100:101] op_sel:[0,0] op_sel_hi:[0,1]
	v_pk_fma_f32 v[24:25], v[10:11], v[102:103], v[24:25] op_sel:[1,0,0] op_sel_hi:[1,1,1]
	v_pk_fma_f32 v[24:25], v[8:9], v[104:105], v[24:25] op_sel:[0,0,0] op_sel_hi:[0,1,1]
	v_pk_fma_f32 v[24:25], v[8:9], v[106:107], v[24:25] op_sel:[1,0,0] op_sel_hi:[1,1,1]
	v_pk_fma_f32 v[16:17], v[108:109], v[162:163], v[10:11] op_sel_hi:[1,0,1]
	v_pk_fma_f32 v[18:19], v[110:111], v[162:163], v[8:9] op_sel_hi:[1,0,1]
	v_add_f32_dpp v15, v24, v24 row_ror:8 row_mask:0xf bank_mask:0xf bound_ctrl:1
	v_add_f32_dpp v33, v25, v25 row_ror:8 row_mask:0xf bank_mask:0xf bound_ctrl:1
	ds_read_b128 v[76:79], v48 offset:24576
	v_add_f32_dpp v15, v15, v15 row_ror:4 row_mask:0xf bank_mask:0xf bound_ctrl:1
	ds_read_b128 v[80:83], v48 offset:24832
	ds_read_b128 v[84:87], v48 offset:25088
	v_add_f32_dpp v15, v15, v15 row_ror:2 row_mask:0xf bank_mask:0xf bound_ctrl:1
	ds_read_b128 v[88:91], v48 offset:25344
	ds_read_b128 v[144:147], v48 offset:33536
	v_add_f32_dpp v30, v15, v15 row_ror:1 row_mask:0xf bank_mask:0xf bound_ctrl:1
	ds_write2st64_b32 v50, v32, v33 offset0:40 offset1:42
	s_waitcnt lgkmcnt(6)
	v_pk_fma_f32 v[10:11], v[112:113], v[30:31], v[16:17] op_sel_hi:[1,0,1] neg_lo:[0,1,0] neg_hi:[0,1,0]
	v_pk_fma_f32 v[8:9], v[114:115], v[30:31], v[18:19] op_sel_hi:[1,0,1] neg_lo:[0,1,0] neg_hi:[0,1,0]
	v_pk_mul_f32 v[24:25], v[10:11], v[116:117] op_sel:[0,0] op_sel_hi:[0,1]
	v_pk_fma_f32 v[24:25], v[10:11], v[118:119], v[24:25] op_sel:[1,0,0] op_sel_hi:[1,1,1]
	v_pk_fma_f32 v[24:25], v[8:9], v[120:121], v[24:25] op_sel:[0,0,0] op_sel_hi:[0,1,1]
	v_pk_fma_f32 v[24:25], v[8:9], v[122:123], v[24:25] op_sel:[1,0,0] op_sel_hi:[1,1,1]
	v_pk_fma_f32 v[16:17], v[124:125], v[162:163], v[10:11] op_sel:[0,1,0] op_sel_hi:[1,1,1]
	v_pk_fma_f32 v[18:19], v[126:127], v[162:163], v[8:9] op_sel:[0,1,0] op_sel_hi:[1,1,1]
	v_add_f32_dpp v15, v24, v24 row_ror:8 row_mask:0xf bank_mask:0xf bound_ctrl:1
	v_add_f32_dpp v32, v25, v25 row_ror:8 row_mask:0xf bank_mask:0xf bound_ctrl:1
	ds_read_b128 v[92:95], v48 offset:25600
	v_add_f32_dpp v15, v15, v15 row_ror:4 row_mask:0xf bank_mask:0xf bound_ctrl:1
	ds_read_b128 v[96:99], v48 offset:25856
	ds_read_b128 v[100:103], v48 offset:26112
	v_add_f32_dpp v15, v15, v15 row_ror:2 row_mask:0xf bank_mask:0xf bound_ctrl:1
	ds_read_b128 v[104:107], v48 offset:26368
	s_nop 0
	v_add_f32_dpp v30, v15, v15 row_ror:1 row_mask:0xf bank_mask:0xf bound_ctrl:1
	s_waitcnt lgkmcnt(4)
	v_pk_fma_f32 v[10:11], v[128:129], v[30:31], v[16:17] op_sel_hi:[1,0,1] neg_lo:[0,1,0] neg_hi:[0,1,0]
	v_pk_fma_f32 v[8:9], v[130:131], v[30:31], v[18:19] op_sel_hi:[1,0,1] neg_lo:[0,1,0] neg_hi:[0,1,0]
	v_pk_mul_f32 v[24:25], v[10:11], v[132:133] op_sel:[0,0] op_sel_hi:[0,1]
	v_pk_fma_f32 v[24:25], v[10:11], v[134:135], v[24:25] op_sel:[1,0,0] op_sel_hi:[1,1,1]
	v_pk_fma_f32 v[24:25], v[8:9], v[136:137], v[24:25] op_sel:[0,0,0] op_sel_hi:[0,1,1]
	v_pk_fma_f32 v[24:25], v[8:9], v[138:139], v[24:25] op_sel:[1,0,0] op_sel_hi:[1,1,1]
	s_nop 1
	v_add_f32_dpp v33, v25, v25 row_ror:8 row_mask:0xf bank_mask:0xf bound_ctrl:1
	ds_write2st64_b32 v50, v32, v33 offset0:44 offset1:46
	v_pk_mul_f32 v[10:11], v[10:11], v[140:141]
	v_pk_mul_f32 v[8:9], v[8:9], v[142:143]
	v_pk_mul_f32 v[24:25], v[10:11], v[144:145]
	v_pk_fma_f32 v[24:25], v[8:9], v[146:147], v[24:25]
	v_add_f32_e32 v24, v24, v25
	v_pk_fma_f32 v[16:17], v[76:77], v[156:157], v[10:11] op_sel_hi:[1,0,1]
	v_pk_fma_f32 v[18:19], v[78:79], v[156:157], v[8:9] op_sel_hi:[1,0,1]
	v_add_f32_dpp v15, v24, v24 row_ror:8 row_mask:0xf bank_mask:0xf bound_ctrl:1
	ds_read_b128 v[108:111], v48 offset:26624
	ds_read_b128 v[112:115], v48 offset:26880
	v_add_f32_dpp v15, v15, v15 row_ror:4 row_mask:0xf bank_mask:0xf bound_ctrl:1
	ds_read_b128 v[116:119], v48 offset:27136
	ds_read_b128 v[120:123], v48 offset:27392
	v_add_f32_dpp v15, v15, v15 row_ror:2 row_mask:0xf bank_mask:0xf bound_ctrl:1
	s_nop 1
	v_add_f32_dpp v30, v15, v15 row_ror:1 row_mask:0xf bank_mask:0xf bound_ctrl:1
	s_waitcnt lgkmcnt(5)
	v_pk_fma_f32 v[10:11], v[80:81], v[30:31], v[16:17] op_sel_hi:[1,0,1] neg_lo:[0,1,0] neg_hi:[0,1,0]
	v_pk_fma_f32 v[8:9], v[82:83], v[30:31], v[18:19] op_sel_hi:[1,0,1] neg_lo:[0,1,0] neg_hi:[0,1,0]
	v_pk_mul_f32 v[24:25], v[10:11], v[84:85] op_sel:[0,0] op_sel_hi:[0,1]
	v_pk_fma_f32 v[24:25], v[10:11], v[86:87], v[24:25] op_sel:[1,0,0] op_sel_hi:[1,1,1]
	v_pk_fma_f32 v[24:25], v[8:9], v[88:89], v[24:25] op_sel:[0,0,0] op_sel_hi:[0,1,1]
	v_pk_fma_f32 v[24:25], v[8:9], v[90:91], v[24:25] op_sel:[1,0,0] op_sel_hi:[1,1,1]
	v_pk_fma_f32 v[16:17], v[92:93], v[156:157], v[10:11] op_sel:[0,1,0] op_sel_hi:[1,1,1]
	v_pk_fma_f32 v[18:19], v[94:95], v[156:157], v[8:9] op_sel:[0,1,0] op_sel_hi:[1,1,1]
	v_add_f32_dpp v15, v24, v24 row_ror:8 row_mask:0xf bank_mask:0xf bound_ctrl:1
	v_add_f32_dpp v32, v25, v25 row_ror:8 row_mask:0xf bank_mask:0xf bound_ctrl:1
	ds_read_b128 v[124:127], v48 offset:27648
	v_add_f32_dpp v15, v15, v15 row_ror:4 row_mask:0xf bank_mask:0xf bound_ctrl:1
	ds_read_b128 v[128:131], v48 offset:27904
	ds_read_b128 v[132:135], v48 offset:28160
	v_add_f32_dpp v15, v15, v15 row_ror:2 row_mask:0xf bank_mask:0xf bound_ctrl:1
	ds_read_b128 v[136:139], v48 offset:28416
	ds_read_b128 v[160:163], v49 offset:112
	v_add_f32_dpp v30, v15, v15 row_ror:1 row_mask:0xf bank_mask:0xf bound_ctrl:1
	s_waitcnt lgkmcnt(5)
	v_pk_fma_f32 v[10:11], v[96:97], v[30:31], v[16:17] op_sel_hi:[1,0,1] neg_lo:[0,1,0] neg_hi:[0,1,0]
	v_pk_fma_f32 v[8:9], v[98:99], v[30:31], v[18:19] op_sel_hi:[1,0,1] neg_lo:[0,1,0] neg_hi:[0,1,0]
	v_pk_mul_f32 v[24:25], v[10:11], v[100:101] op_sel:[0,0] op_sel_hi:[0,1]
	v_pk_fma_f32 v[24:25], v[10:11], v[102:103], v[24:25] op_sel:[1,0,0] op_sel_hi:[1,1,1]
	v_pk_fma_f32 v[24:25], v[8:9], v[104:105], v[24:25] op_sel:[0,0,0] op_sel_hi:[0,1,1]
	v_pk_fma_f32 v[24:25], v[8:9], v[106:107], v[24:25] op_sel:[1,0,0] op_sel_hi:[1,1,1]
	v_pk_fma_f32 v[16:17], v[108:109], v[158:159], v[10:11] op_sel_hi:[1,0,1]
	v_pk_fma_f32 v[18:19], v[110:111], v[158:159], v[8:9] op_sel_hi:[1,0,1]
	v_add_f32_dpp v15, v24, v24 row_ror:8 row_mask:0xf bank_mask:0xf bound_ctrl:1
	v_add_f32_dpp v33, v25, v25 row_ror:8 row_mask:0xf bank_mask:0xf bound_ctrl:1
	ds_read_b128 v[76:79], v48 offset:28672
	v_add_f32_dpp v15, v15, v15 row_ror:4 row_mask:0xf bank_mask:0xf bound_ctrl:1
	ds_read_b128 v[80:83], v48 offset:28928
	ds_read_b128 v[84:87], v48 offset:29184
	v_add_f32_dpp v15, v15, v15 row_ror:2 row_mask:0xf bank_mask:0xf bound_ctrl:1
	ds_read_b128 v[88:91], v48 offset:29440
	s_nop 0
	v_add_f32_dpp v30, v15, v15 row_ror:1 row_mask:0xf bank_mask:0xf bound_ctrl:1
	ds_write2st64_b32 v50, v32, v33 offset0:48 offset1:50
	ds_read_b128 v[56:59], v52
	s_waitcnt lgkmcnt(5)
	v_pk_fma_f32 v[10:11], v[112:113], v[30:31], v[16:17] op_sel_hi:[1,0,1] neg_lo:[0,1,0] neg_hi:[0,1,0]
	v_pk_fma_f32 v[8:9], v[114:115], v[30:31], v[18:19] op_sel_hi:[1,0,1] neg_lo:[0,1,0] neg_hi:[0,1,0]
	v_pk_mul_f32 v[24:25], v[10:11], v[116:117] op_sel:[0,0] op_sel_hi:[0,1]
	v_pk_fma_f32 v[24:25], v[10:11], v[118:119], v[24:25] op_sel:[1,0,0] op_sel_hi:[1,1,1]
	v_pk_fma_f32 v[24:25], v[8:9], v[120:121], v[24:25] op_sel:[0,0,0] op_sel_hi:[0,1,1]
	v_pk_fma_f32 v[24:25], v[8:9], v[122:123], v[24:25] op_sel:[1,0,0] op_sel_hi:[1,1,1]
	v_pk_fma_f32 v[16:17], v[124:125], v[158:159], v[10:11] op_sel:[0,1,0] op_sel_hi:[1,1,1]
	v_pk_fma_f32 v[18:19], v[126:127], v[158:159], v[8:9] op_sel:[0,1,0] op_sel_hi:[1,1,1]
	v_add_f32_dpp v15, v24, v24 row_ror:8 row_mask:0xf bank_mask:0xf bound_ctrl:1
	v_add_f32_dpp v32, v25, v25 row_ror:8 row_mask:0xf bank_mask:0xf bound_ctrl:1
	ds_read_b128 v[92:95], v48 offset:29696
	v_add_f32_dpp v15, v15, v15 row_ror:4 row_mask:0xf bank_mask:0xf bound_ctrl:1
	ds_read_b128 v[96:99], v48 offset:29952
	ds_read_b128 v[100:103], v48 offset:30208
	v_add_f32_dpp v15, v15, v15 row_ror:2 row_mask:0xf bank_mask:0xf bound_ctrl:1
	ds_read_b128 v[104:107], v48 offset:30464
	s_nop 0
	v_add_f32_dpp v30, v15, v15 row_ror:1 row_mask:0xf bank_mask:0xf bound_ctrl:1
	s_waitcnt lgkmcnt(4)
	v_min_u32_e32 v56, v56, v57
	v_min3_u32 v56, v56, v58, v59
	v_pk_fma_f32 v[10:11], v[128:129], v[30:31], v[16:17] op_sel_hi:[1,0,1] neg_lo:[0,1,0] neg_hi:[0,1,0]
	v_pk_fma_f32 v[8:9], v[130:131], v[30:31], v[18:19] op_sel_hi:[1,0,1] neg_lo:[0,1,0] neg_hi:[0,1,0]
	v_pk_mul_f32 v[24:25], v[10:11], v[132:133] op_sel:[0,0] op_sel_hi:[0,1]
	v_pk_fma_f32 v[24:25], v[10:11], v[134:135], v[24:25] op_sel:[1,0,0] op_sel_hi:[1,1,1]
	v_pk_fma_f32 v[24:25], v[8:9], v[136:137], v[24:25] op_sel:[0,0,0] op_sel_hi:[0,1,1]
	v_pk_fma_f32 v[24:25], v[8:9], v[138:139], v[24:25] op_sel:[1,0,0] op_sel_hi:[1,1,1]
	v_pk_fma_f32 v[16:17], v[76:77], v[160:161], v[10:11] op_sel_hi:[1,0,1]
	v_pk_fma_f32 v[18:19], v[78:79], v[160:161], v[8:9] op_sel_hi:[1,0,1]
	v_add_f32_dpp v15, v24, v24 row_ror:8 row_mask:0xf bank_mask:0xf bound_ctrl:1
	v_add_f32_dpp v33, v25, v25 row_ror:8 row_mask:0xf bank_mask:0xf bound_ctrl:1
	ds_read_b128 v[108:111], v48 offset:30720
	v_add_f32_dpp v15, v15, v15 row_ror:4 row_mask:0xf bank_mask:0xf bound_ctrl:1
	ds_read_b128 v[112:115], v48 offset:30976
	ds_read_b128 v[116:119], v48 offset:31232
	v_add_f32_dpp v15, v15, v15 row_ror:2 row_mask:0xf bank_mask:0xf bound_ctrl:1
	ds_read_b128 v[120:123], v48 offset:31488
	ds_read_b128 v[140:143], v48 offset:34560
	v_add_f32_dpp v30, v15, v15 row_ror:1 row_mask:0xf bank_mask:0xf bound_ctrl:1
	ds_write2st64_b32 v50, v32, v33 offset0:52 offset1:54
	s_waitcnt lgkmcnt(6)
	v_pk_fma_f32 v[10:11], v[80:81], v[30:31], v[16:17] op_sel_hi:[1,0,1] neg_lo:[0,1,0] neg_hi:[0,1,0]
	v_pk_fma_f32 v[8:9], v[82:83], v[30:31], v[18:19] op_sel_hi:[1,0,1] neg_lo:[0,1,0] neg_hi:[0,1,0]
	v_pk_mul_f32 v[24:25], v[10:11], v[84:85] op_sel:[0,0] op_sel_hi:[0,1]
	v_pk_fma_f32 v[24:25], v[10:11], v[86:87], v[24:25] op_sel:[1,0,0] op_sel_hi:[1,1,1]
	v_pk_fma_f32 v[24:25], v[8:9], v[88:89], v[24:25] op_sel:[0,0,0] op_sel_hi:[0,1,1]
	v_pk_fma_f32 v[24:25], v[8:9], v[90:91], v[24:25] op_sel:[1,0,0] op_sel_hi:[1,1,1]
	v_pk_fma_f32 v[16:17], v[92:93], v[160:161], v[10:11] op_sel:[0,1,0] op_sel_hi:[1,1,1]
	v_pk_fma_f32 v[18:19], v[94:95], v[160:161], v[8:9] op_sel:[0,1,0] op_sel_hi:[1,1,1]
	v_add_f32_dpp v15, v24, v24 row_ror:8 row_mask:0xf bank_mask:0xf bound_ctrl:1
	v_add_f32_dpp v32, v25, v25 row_ror:8 row_mask:0xf bank_mask:0xf bound_ctrl:1
	ds_read_b128 v[124:127], v48 offset:31744
	v_add_f32_dpp v15, v15, v15 row_ror:4 row_mask:0xf bank_mask:0xf bound_ctrl:1
	ds_read_b128 v[128:131], v48 offset:32000
	ds_read_b128 v[132:135], v48 offset:32256
	v_add_f32_dpp v15, v15, v15 row_ror:2 row_mask:0xf bank_mask:0xf bound_ctrl:1
	ds_read_b128 v[136:139], v48 offset:32512
	s_nop 0
	v_add_f32_dpp v30, v15, v15 row_ror:1 row_mask:0xf bank_mask:0xf bound_ctrl:1
	v_readfirstlane_b32 s54, v56
	s_add_u32 s64, s6, 2
	s_cmp_lt_u32 s54, s64
	s_cbranch_scc1 .Lss_spin_1
.Lss_ok_1:
	s_waitcnt lgkmcnt(4)
	v_pk_fma_f32 v[10:11], v[96:97], v[30:31], v[16:17] op_sel_hi:[1,0,1] neg_lo:[0,1,0] neg_hi:[0,1,0]
	v_pk_fma_f32 v[8:9], v[98:99], v[30:31], v[18:19] op_sel_hi:[1,0,1] neg_lo:[0,1,0] neg_hi:[0,1,0]
	v_pk_mul_f32 v[24:25], v[10:11], v[100:101] op_sel:[0,0] op_sel_hi:[0,1]
	v_pk_fma_f32 v[24:25], v[10:11], v[102:103], v[24:25] op_sel:[1,0,0] op_sel_hi:[1,1,1]
	v_pk_fma_f32 v[24:25], v[8:9], v[104:105], v[24:25] op_sel:[0,0,0] op_sel_hi:[0,1,1]
	v_pk_fma_f32 v[24:25], v[8:9], v[106:107], v[24:25] op_sel:[1,0,0] op_sel_hi:[1,1,1]
	v_pk_fma_f32 v[16:17], v[108:109], v[162:163], v[10:11] op_sel_hi:[1,0,1]
	v_pk_fma_f32 v[18:19], v[110:111], v[162:163], v[8:9] op_sel_hi:[1,0,1]
	v_add_f32_dpp v15, v24, v24 row_ror:8 row_mask:0xf bank_mask:0xf bound_ctrl:1
	v_add_f32_dpp v33, v25, v25 row_ror:8 row_mask:0xf bank_mask:0xf bound_ctrl:1
	ds_read_b128 v[76:79], v34 offset:0
	v_add_f32_dpp v15, v15, v15 row_ror:4 row_mask:0xf bank_mask:0xf bound_ctrl:1
	ds_read_b128 v[80:83], v34 offset:256
	ds_read_b128 v[84:87], v34 offset:512
	v_add_f32_dpp v15, v15, v15 row_ror:2 row_mask:0xf bank_mask:0xf bound_ctrl:1
	ds_read_b128 v[88:91], v34 offset:768
	ds_read_b128 v[144:147], v34 offset:32768
	v_add_f32_dpp v30, v15, v15 row_ror:1 row_mask:0xf bank_mask:0xf bound_ctrl:1
	ds_write2st64_b32 v50, v32, v33 offset0:56 offset1:58
	ds_read_b128 v[156:159], v35 offset:0
	s_waitcnt lgkmcnt(7)
	v_pk_fma_f32 v[10:11], v[112:113], v[30:31], v[16:17] op_sel_hi:[1,0,1] neg_lo:[0,1,0] neg_hi:[0,1,0]
	v_pk_fma_f32 v[8:9], v[114:115], v[30:31], v[18:19] op_sel_hi:[1,0,1] neg_lo:[0,1,0] neg_hi:[0,1,0]
	v_pk_mul_f32 v[24:25], v[10:11], v[116:117] op_sel:[0,0] op_sel_hi:[0,1]
	v_pk_fma_f32 v[24:25], v[10:11], v[118:119], v[24:25] op_sel:[1,0,0] op_sel_hi:[1,1,1]
	v_pk_fma_f32 v[24:25], v[8:9], v[120:121], v[24:25] op_sel:[0,0,0] op_sel_hi:[0,1,1]
	v_pk_fma_f32 v[24:25], v[8:9], v[122:123], v[24:25] op_sel:[1,0,0] op_sel_hi:[1,1,1]
	v_pk_fma_f32 v[16:17], v[124:125], v[162:163], v[10:11] op_sel:[0,1,0] op_sel_hi:[1,1,1]
	v_pk_fma_f32 v[18:19], v[126:127], v[162:163], v[8:9] op_sel:[0,1,0] op_sel_hi:[1,1,1]
	v_add_f32_dpp v15, v24, v24 row_ror:8 row_mask:0xf bank_mask:0xf bound_ctrl:1
	v_add_f32_dpp v32, v25, v25 row_ror:8 row_mask:0xf bank_mask:0xf bound_ctrl:1
	ds_read_b128 v[92:95], v34 offset:1024
	v_add_f32_dpp v15, v15, v15 row_ror:4 row_mask:0xf bank_mask:0xf bound_ctrl:1
	ds_read_b128 v[96:99], v34 offset:1280
	ds_read_b128 v[100:103], v34 offset:1536
	v_add_f32_dpp v15, v15, v15 row_ror:2 row_mask:0xf bank_mask:0xf bound_ctrl:1
	ds_read_b128 v[104:107], v34 offset:1792
	s_nop 0
	v_add_f32_dpp v30, v15, v15 row_ror:1 row_mask:0xf bank_mask:0xf bound_ctrl:1
	s_waitcnt lgkmcnt(4)
	v_pk_fma_f32 v[10:11], v[128:129], v[30:31], v[16:17] op_sel_hi:[1,0,1] neg_lo:[0,1,0] neg_hi:[0,1,0]
	v_pk_fma_f32 v[8:9], v[130:131], v[30:31], v[18:19] op_sel_hi:[1,0,1] neg_lo:[0,1,0] neg_hi:[0,1,0]
	v_pk_mul_f32 v[24:25], v[10:11], v[132:133] op_sel:[0,0] op_sel_hi:[0,1]
	v_pk_fma_f32 v[24:25], v[10:11], v[134:135], v[24:25] op_sel:[1,0,0] op_sel_hi:[1,1,1]
	v_pk_fma_f32 v[24:25], v[8:9], v[136:137], v[24:25] op_sel:[0,0,0] op_sel_hi:[0,1,1]
	v_pk_fma_f32 v[24:25], v[8:9], v[138:139], v[24:25] op_sel:[1,0,0] op_sel_hi:[1,1,1]
	s_nop 1
	v_add_f32_dpp v33, v25, v25 row_ror:8 row_mask:0xf bank_mask:0xf bound_ctrl:1
	ds_write2st64_b32 v50, v32, v33 offset0:60 offset1:62
	v_pk_mul_f32 v[10:11], v[10:11], v[140:141]
	v_pk_mul_f32 v[8:9], v[8:9], v[142:143]
	v_pk_mul_f32 v[24:25], v[10:11], v[144:145]
	v_pk_fma_f32 v[24:25], v[8:9], v[146:147], v[24:25]
	v_add_f32_e32 v24, v24, v25
	v_pk_fma_f32 v[16:17], v[76:77], v[156:157], v[10:11] op_sel_hi:[1,0,1]
	v_pk_fma_f32 v[18:19], v[78:79], v[156:157], v[8:9] op_sel_hi:[1,0,1]
	v_add_f32_dpp v15, v24, v24 row_ror:8 row_mask:0xf bank_mask:0xf bound_ctrl:1
	v_add_u32_e32 v51, 1, v51
	s_add_u32 s6, s6, 1
	v_add_f32_dpp v15, v15, v15 row_ror:4 row_mask:0xf bank_mask:0xf bound_ctrl:1
	ds_write_b32 v53, v51
	ds_read_b128 v[108:111], v34 offset:2048
	v_add_f32_dpp v15, v15, v15 row_ror:2 row_mask:0xf bank_mask:0xf bound_ctrl:1
	ds_read_b128 v[112:115], v34 offset:2304
	ds_read_b128 v[116:119], v34 offset:2560
	v_add_f32_dpp v30, v15, v15 row_ror:1 row_mask:0xf bank_mask:0xf bound_ctrl:1
	ds_read_b128 v[120:123], v34 offset:2816
	s_cmp_lt_u32 s6, 0x100
	s_cbranch_scc1 .Lsc_S_loop
	s_waitcnt lgkmcnt(0)
	s_branch .Lsc_item_end
	s_nop 0
	s_nop 0
	s_nop 0
	s_nop 0
	s_nop 0
	s_nop 0
	s_nop 0
	s_nop 0
	s_nop 0
	s_nop 0
	s_nop 0
	s_nop 0
	s_nop 0
	s_nop 0
	s_nop 0
	s_nop 0
	s_nop 0

.Lsc_G_poll0:
	ds_read_b128 v[148:151], v144
	s_waitcnt lgkmcnt(0)
	v_min_u32_e32 v148, v148, v149
	v_min3_u32 v148, v148, v150, v151
	s_sub_u32 s69, s69, 1
	s_nop 1
	v_readfirstlane_b32 s68, v148
	s_cmp_eq_u32 s69, 0
	s_cbranch_scc1 .Lsc_G_go0
	s_cmp_ge_u32 s68, s65
	s_cbranch_scc1 .Lsc_G_go0
	s_sleep 8
	s_branch .Lsc_G_poll0
